# P0a transposes: nt (non-temporal) hint on the converted-weight stores, on the v042 stack
# baseline (speedup 1.0000x reference)
.LBB0_18:
	s_lshl_b32 s11, s8, 1
	s_lshl_b32 s10, s7, 1
	v_or_b32_e32 v34, s11, v4
	s_add_i32 s27, s11, 4
	v_mov_b32_e32 v7, v35
	v_or_b32_e32 v6, s10, v5
	s_add_i32 s26, s10, 4
	s_add_i32 s37, s11, 8
	v_lshlrev_b64 v[22:23], 14, v[34:35]
	v_or_b32_e32 v34, s27, v4
	v_mov_b32_e32 v9, v35
	s_add_i32 s36, s10, 8
	s_add_i32 s45, s11, 12
	v_lshlrev_b64 v[6:7], 14, v[6:7]
	v_or_b32_e32 v8, s26, v5
	v_lshlrev_b64 v[24:25], 14, v[34:35]
	v_or_b32_e32 v34, s37, v4
	v_mov_b32_e32 v11, v35
	s_add_i32 s44, s10, 12
	s_add_i32 s49, s11, 16
	v_or_b32_e32 v10, s36, v5
	v_lshl_add_u64 v[22:23], v[2:3], 0, v[22:23]
	v_lshl_add_u64 v[6:7], v[2:3], 0, v[6:7]
	v_lshlrev_b64 v[8:9], 14, v[8:9]
	v_lshl_add_u64 v[24:25], v[2:3], 0, v[24:25]
	v_lshlrev_b64 v[26:27], 14, v[34:35]
	v_or_b32_e32 v34, s45, v4
	v_mov_b32_e32 v13, v35
	s_add_i32 s47, s10, 16
	s_add_i32 s50, s10, 20
	s_add_i32 s51, s11, 20
	v_or_b32_e32 v12, s44, v5
	v_lshlrev_b64 v[10:11], 14, v[10:11]
	v_lshl_add_u64 v[8:9], v[2:3], 0, v[8:9]
	global_load_dword v22, v[22:23], off
	s_nop 0
	global_load_dword v23, v[6:7], off
	s_nop 0
	global_load_dword v6, v[24:25], off
	global_load_dword v7, v[8:9], off
	v_lshlrev_b64 v[24:25], 14, v[34:35]
	v_or_b32_e32 v34, s49, v4
	v_mov_b32_e32 v15, v35
	v_mov_b32_e32 v17, v35
	s_add_i32 s52, s10, 24
	s_add_i32 s53, s11, 24
	v_or_b32_e32 v14, s47, v5
	v_or_b32_e32 v16, s50, v5
	v_lshlrev_b64 v[12:13], 14, v[12:13]
	v_lshl_add_u64 v[10:11], v[2:3], 0, v[10:11]
	v_lshl_add_u64 v[8:9], v[2:3], 0, v[26:27]
	v_lshl_add_u64 v[24:25], v[2:3], 0, v[24:25]
	v_lshlrev_b64 v[26:27], 14, v[34:35]
	v_or_b32_e32 v34, s51, v4
	v_mov_b32_e32 v19, v35
	s_add_i32 s55, s11, 28
	v_or_b32_e32 v18, s52, v5
	v_lshlrev_b64 v[14:15], 14, v[14:15]
	v_lshlrev_b64 v[16:17], 14, v[16:17]
	v_lshl_add_u64 v[12:13], v[2:3], 0, v[12:13]
	global_load_dword v8, v[8:9], off
	s_nop 0
	global_load_dword v9, v[10:11], off
	s_nop 0
	global_load_dword v10, v[24:25], off
	global_load_dword v11, v[12:13], off
	v_lshlrev_b64 v[24:25], 14, v[34:35]
	v_or_b32_e32 v34, s53, v4
	s_add_i32 s54, s10, 28
	v_lshlrev_b64 v[18:19], 14, v[18:19]
	v_lshl_add_u64 v[14:15], v[2:3], 0, v[14:15]
	v_lshl_add_u64 v[16:17], v[2:3], 0, v[16:17]
	v_lshl_add_u64 v[12:13], v[2:3], 0, v[26:27]
	v_lshl_add_u64 v[24:25], v[2:3], 0, v[24:25]
	v_lshlrev_b64 v[26:27], 14, v[34:35]
	v_or_b32_e32 v34, s55, v4
	v_mov_b32_e32 v21, v35
	v_or_b32_e32 v20, s54, v5
	v_lshl_add_u64 v[18:19], v[2:3], 0, v[18:19]
	global_load_dword v12, v[12:13], off
	s_nop 0
	global_load_dword v13, v[14:15], off
	s_nop 0
	global_load_dword v14, v[24:25], off
	global_load_dword v15, v[16:17], off
	v_lshl_add_u64 v[16:17], v[2:3], 0, v[26:27]
	v_lshlrev_b64 v[24:25], 14, v[34:35]
	v_lshlrev_b64 v[20:21], 14, v[20:21]
	global_load_dword v16, v[16:17], off
	s_nop 0
	global_load_dword v17, v[18:19], off
	v_lshl_add_u64 v[18:19], v[2:3], 0, v[24:25]
	v_lshl_add_u64 v[20:21], v[2:3], 0, v[20:21]
	global_load_dword v18, v[18:19], off
	s_nop 0
	global_load_dword v19, v[20:21], off
	v_or_b32_e32 v24, s10, v1
	v_or_b32_e32 v20, s11, v38
	v_mad_u64_u32 v[24:25], s[10:11], v24, s21, v[44:45]
	v_mad_u64_u32 v[20:21], s[10:11], v20, s21, v[44:45]
	v_or_b32_e32 v25, s27, v38
	v_or_b32_e32 v21, s26, v1
	v_or_b32_e32 v30, s37, v38
	v_mad_u64_u32 v[26:27], s[10:11], v25, s21, v[44:45]
	v_or_b32_e32 v32, s36, v1
	v_or_b32_e32 v61, s45, v38
	v_mad_u64_u32 v[28:29], s[10:11], v21, s21, v[44:45]
	v_mad_u64_u32 v[30:31], s[10:11], v30, s21, v[44:45]
	v_or_b32_e32 v34, s44, v1
	v_or_b32_e32 v84, s49, v38
	v_mad_u64_u32 v[32:33], s[10:11], v32, s21, v[44:45]
	v_mad_u64_u32 v[80:81], s[10:11], v61, s21, v[44:45]
	v_or_b32_e32 v79, s47, v1
	v_or_b32_e32 v88, s51, v38
	v_mad_u64_u32 v[82:83], s[10:11], v34, s21, v[44:45]
	v_mad_u64_u32 v[84:85], s[10:11], v84, s21, v[44:45]
	v_or_b32_e32 v90, s50, v1
	v_or_b32_e32 v92, s53, v38
	v_mad_u64_u32 v[86:87], s[10:11], v79, s21, v[44:45]
	v_mad_u64_u32 v[88:89], s[10:11], v88, s21, v[44:45]
	s_waitcnt vmcnt(14)
	v_pk_mul_f32 v[22:23], v[22:23], s[20:21] op_sel_hi:[1,0]
	ds_write_b32 v20, v22
	ds_write_b32 v24, v23
	s_waitcnt vmcnt(12)
	v_pk_mul_f32 v[6:7], v[6:7], s[20:21] op_sel_hi:[1,0]
	ds_write_b32 v26, v6
	ds_write_b32 v28, v7
	s_add_i32 s8, s8, 16
	s_add_i32 s7, s7, 16
	s_add_i32 s9, s9, -16
	v_or_b32_e32 v94, s52, v1
	v_or_b32_e32 v96, s55, v38
	v_mad_u64_u32 v[90:91], s[10:11], v90, s21, v[44:45]
	v_mad_u64_u32 v[92:93], s[10:11], v92, s21, v[44:45]
	v_or_b32_e32 v98, s54, v1
	s_cmp_lg_u32 s9, 0
	v_mad_u64_u32 v[94:95], s[10:11], v94, s21, v[44:45]
	v_mad_u64_u32 v[96:97], s[10:11], v96, s21, v[44:45]
	v_mad_u64_u32 v[98:99], s[10:11], v98, s21, v[44:45]
	s_waitcnt vmcnt(10)
	v_pk_mul_f32 v[6:7], v[8:9], s[20:21] op_sel_hi:[1,0]
	ds_write_b32 v30, v6
	ds_write_b32 v32, v7
	s_waitcnt vmcnt(8)
	v_pk_mul_f32 v[6:7], v[10:11], s[20:21] op_sel_hi:[1,0]
	ds_write_b32 v80, v6
	ds_write_b32 v82, v7
	s_waitcnt vmcnt(6)
	v_pk_mul_f32 v[6:7], v[12:13], s[20:21] op_sel_hi:[1,0]
	ds_write_b32 v84, v6
	ds_write_b32 v86, v7
	s_waitcnt vmcnt(4)
	v_pk_mul_f32 v[6:7], v[14:15], s[20:21] op_sel_hi:[1,0]
	ds_write_b32 v88, v6
	ds_write_b32 v90, v7
	s_waitcnt vmcnt(2)
	v_pk_mul_f32 v[6:7], v[16:17], s[20:21] op_sel_hi:[1,0]
	ds_write_b32 v92, v6
	ds_write_b32 v94, v7
	s_waitcnt vmcnt(0)
	v_pk_mul_f32 v[6:7], v[18:19], s[20:21] op_sel_hi:[1,0]
	ds_write_b32 v96, v6
	ds_write_b32 v98, v7
	s_cbranch_scc1 .LBB0_18
	s_waitcnt lgkmcnt(0)
	ds_read2_b32 v[6:7], v59 offset1:16
	ds_read2_b32 v[8:9], v59 offset0:33 offset1:49
	ds_read2_b32 v[10:11], v59 offset0:66 offset1:82
	ds_read2_b32 v[12:13], v59 offset0:99 offset1:115
	ds_read2_b32 v[16:17], v59 offset0:132 offset1:148
	ds_read2_b32 v[18:19], v59 offset0:165 offset1:181
	ds_read2_b32 v[20:21], v59 offset0:198 offset1:214
	ds_read2_b32 v[22:23], v59 offset0:231 offset1:247
	s_waitcnt lgkmcnt(7)
	v_max_f32_e32 v2, v6, v6
	s_waitcnt lgkmcnt(6)
	v_max_f32_e32 v3, v8, v8
	v_med3_f32 v6, v2, s39, v77
	v_med3_f32 v3, v3, s39, v77
	v_mov_b32_e32 v2, v35
	v_cvt_pk_fp8_f32 v2, v6, v3
	s_waitcnt lgkmcnt(5)
	v_max_f32_e32 v4, v10, v10
	s_waitcnt lgkmcnt(4)
	v_max_f32_e32 v5, v12, v12
	v_med3_f32 v4, v4, s39, v77
	v_med3_f32 v5, v5, s39, v77
	v_cvt_pk_fp8_f32 v2, v4, v5 op_sel:[0,0,1]
	s_waitcnt lgkmcnt(3)
	v_max_f32_e32 v3, v16, v16
	s_waitcnt lgkmcnt(2)
	v_max_f32_e32 v4, v18, v18
	v_med3_f32 v8, v3, s39, v77
	v_med3_f32 v4, v4, s39, v77
	v_mov_b32_e32 v3, v35
	v_cvt_pk_fp8_f32 v3, v8, v4
	v_add_u32_e32 v8, 0x400, v59
	ds_read2_b32 v[24:25], v8 offset0:8 offset1:24
	ds_read2_b32 v[26:27], v8 offset0:41 offset1:57
	ds_read2_b32 v[28:29], v8 offset0:74 offset1:90
	ds_read2_b32 v[30:31], v8 offset0:107 offset1:123
	s_waitcnt lgkmcnt(5)
	v_max_f32_e32 v5, v20, v20
	s_waitcnt lgkmcnt(4)
	v_max_f32_e32 v6, v22, v22
	v_med3_f32 v5, v5, s39, v77
	v_med3_f32 v6, v6, s39, v77
	v_cvt_pk_fp8_f32 v3, v5, v6 op_sel:[0,0,1]
	s_waitcnt lgkmcnt(3)
	v_max_f32_e32 v4, v24, v24
	s_waitcnt lgkmcnt(2)
	v_max_f32_e32 v5, v26, v26
	v_med3_f32 v12, v4, s39, v77
	v_med3_f32 v5, v5, s39, v77
	v_mov_b32_e32 v4, v35
	v_cvt_pk_fp8_f32 v4, v12, v5
	ds_read2_b32 v[32:33], v8 offset0:140 offset1:156
	ds_read2_b32 v[80:81], v8 offset0:173 offset1:189
	ds_read2_b32 v[82:83], v8 offset0:206 offset1:222
	s_waitcnt lgkmcnt(4)
	v_max_f32_e32 v6, v28, v28
	s_waitcnt lgkmcnt(3)
	v_max_f32_e32 v10, v30, v30
	v_med3_f32 v6, v6, s39, v77
	v_med3_f32 v5, v10, s39, v77
	ds_read2_b32 v[84:85], v8 offset0:239 offset1:255
	v_cvt_pk_fp8_f32 v4, v6, v5 op_sel:[0,0,1]
	s_waitcnt lgkmcnt(3)
	v_max_f32_e32 v5, v32, v32
	s_waitcnt lgkmcnt(2)
	v_max_f32_e32 v6, v80, v80
	v_med3_f32 v8, v5, s39, v77
	v_med3_f32 v6, v6, s39, v77
	v_mov_b32_e32 v5, v35
	v_cvt_pk_fp8_f32 v5, v8, v6
	s_waitcnt lgkmcnt(1)
	v_max_f32_e32 v10, v82, v82
	s_waitcnt lgkmcnt(0)
	v_max_f32_e32 v6, v84, v84
	v_med3_f32 v8, v10, s39, v77
	v_med3_f32 v6, v6, s39, v77
	v_cvt_pk_fp8_f32 v5, v8, v6 op_sel:[0,0,1]
	v_or_b32_e32 v6, s6, v45
	v_lshl_add_u64 v[14:15], v[46:47], 0, s[16:17]
	v_lshlrev_b32_e32 v34, 14, v6
	v_lshl_add_u64 v[86:87], v[14:15], 0, v[34:35]
	global_store_dwordx4 v[86:87], v[2:5], off nt
	s_nop 1
	v_max_f32_e32 v2, v7, v7
	v_max_f32_e32 v3, v9, v9
	v_med3_f32 v5, v2, s39, v77
	v_med3_f32 v3, v3, s39, v77
	v_mov_b32_e32 v2, v35
	v_cvt_pk_fp8_f32 v2, v5, v3
	v_max_f32_e32 v4, v11, v11
	v_max_f32_e32 v3, v13, v13
	v_med3_f32 v4, v4, s39, v77
	v_med3_f32 v3, v3, s39, v77
	v_cvt_pk_fp8_f32 v2, v4, v3 op_sel:[0,0,1]
	v_max_f32_e32 v3, v17, v17
	v_max_f32_e32 v4, v19, v19
	v_med3_f32 v6, v3, s39, v77
	v_med3_f32 v4, v4, s39, v77
	v_mov_b32_e32 v3, v35
	v_cvt_pk_fp8_f32 v3, v6, v4
	v_max_f32_e32 v5, v21, v21
	v_max_f32_e32 v4, v23, v23
	v_med3_f32 v5, v5, s39, v77
	v_med3_f32 v4, v4, s39, v77
	v_cvt_pk_fp8_f32 v3, v5, v4 op_sel:[0,0,1]
	v_max_f32_e32 v4, v25, v25
	v_max_f32_e32 v5, v27, v27
	v_med3_f32 v7, v4, s39, v77
	v_med3_f32 v5, v5, s39, v77
	v_mov_b32_e32 v4, v35
	v_cvt_pk_fp8_f32 v4, v7, v5
	v_max_f32_e32 v6, v29, v29
	v_max_f32_e32 v5, v31, v31
	v_med3_f32 v6, v6, s39, v77
	v_med3_f32 v5, v5, s39, v77
	v_cvt_pk_fp8_f32 v4, v6, v5 op_sel:[0,0,1]
	v_max_f32_e32 v5, v33, v33
	v_max_f32_e32 v6, v81, v81
	v_med3_f32 v8, v5, s39, v77
	v_med3_f32 v6, v6, s39, v77
	v_mov_b32_e32 v5, v35
	v_cvt_pk_fp8_f32 v5, v8, v6
	v_max_f32_e32 v7, v83, v83
	v_max_f32_e32 v6, v85, v85
	v_med3_f32 v7, v7, s39, v77
	v_med3_f32 v6, v6, s39, v77
	v_cvt_pk_fp8_f32 v5, v7, v6 op_sel:[0,0,1]
	v_or_b32_e32 v6, s6, v62
	v_lshlrev_b32_e32 v34, 14, v6
	v_lshl_add_u64 v[6:7], v[14:15], 0, v[34:35]
	global_store_dwordx4 v[6:7], v[2:5], off nt
	s_waitcnt lgkmcnt(0)
	s_mov_b64 s[6:7], 0

.LBB0_22:
	s_lshl_b32 s11, s8, 1
	s_lshl_b32 s16, s9, 1
	v_or_b32_e32 v34, s16, v4
	s_add_i32 s36, s11, 4
	s_add_i32 s37, s16, 4
	v_mov_b32_e32 v9, v35
	s_add_i32 s45, s16, 8
	v_lshlrev_b64 v[22:23], 16, v[34:35]
	v_or_b32_e32 v8, s36, v5
	v_or_b32_e32 v34, s37, v4
	v_mov_b32_e32 v7, v35
	v_or_b32_e32 v6, s11, v5
	s_add_i32 s49, s16, 12
	v_lshlrev_b64 v[8:9], 16, v[8:9]
	v_lshlrev_b64 v[24:25], 16, v[34:35]
	v_or_b32_e32 v34, s45, v4
	s_add_i32 s44, s11, 8
	s_add_i32 s47, s11, 12
	s_add_i32 s51, s16, 16
	v_lshlrev_b64 v[6:7], 16, v[6:7]
	v_lshl_add_u64 v[22:23], v[2:3], 0, v[22:23]
	v_lshl_add_u64 v[8:9], v[2:3], 0, v[8:9]
	v_lshlrev_b64 v[26:27], 16, v[34:35]
	v_or_b32_e32 v34, s49, v4
	v_mov_b32_e32 v11, v35
	v_mov_b32_e32 v13, v35
	s_add_i32 s53, s16, 20
	v_or_b32_e32 v10, s44, v5
	v_or_b32_e32 v12, s47, v5
	v_lshl_add_u64 v[6:7], v[2:3], 0, v[6:7]
	v_lshl_add_u64 v[24:25], v[2:3], 0, v[24:25]
	global_load_dword v61, v[22:23], off
	global_load_dword v79, v[6:7], off
	global_load_dword v84, v[24:25], off
	global_load_dword v85, v[8:9], off
	v_lshlrev_b64 v[8:9], 16, v[34:35]
	v_or_b32_e32 v34, s51, v4
	s_add_i32 s50, s11, 16
	s_add_i32 s52, s11, 20
	s_add_i32 s55, s16, 24
	v_lshlrev_b64 v[10:11], 16, v[10:11]
	v_lshlrev_b64 v[12:13], 16, v[12:13]
	v_lshl_add_u64 v[6:7], v[2:3], 0, v[26:27]
	v_lshl_add_u64 v[8:9], v[2:3], 0, v[8:9]
	v_lshlrev_b64 v[22:23], 16, v[34:35]
	v_or_b32_e32 v34, s53, v4
	v_mov_b32_e32 v15, v35
	v_mov_b32_e32 v17, v35
	s_add_i32 s54, s11, 24
	s_add_i32 s56, s11, 28
	s_add_i32 s57, s16, 28
	v_or_b32_e32 v14, s50, v5
	v_or_b32_e32 v16, s52, v5
	v_lshl_add_u64 v[10:11], v[2:3], 0, v[10:11]
	v_lshl_add_u64 v[12:13], v[2:3], 0, v[12:13]
	global_load_dword v86, v[6:7], off
	global_load_dword v87, v[10:11], off
	global_load_dword v88, v[8:9], off
	global_load_dword v89, v[12:13], off
	v_lshlrev_b64 v[8:9], 16, v[34:35]
	v_or_b32_e32 v34, s55, v4
	v_mov_b32_e32 v19, v35
	v_mov_b32_e32 v21, v35
	v_or_b32_e32 v18, s54, v5
	v_or_b32_e32 v20, s56, v5
	v_lshlrev_b64 v[14:15], 16, v[14:15]
	v_lshlrev_b64 v[16:17], 16, v[16:17]
	v_lshl_add_u64 v[6:7], v[2:3], 0, v[22:23]
	v_lshl_add_u64 v[8:9], v[2:3], 0, v[8:9]
	v_lshlrev_b64 v[10:11], 16, v[34:35]
	v_or_b32_e32 v34, s57, v4
	v_lshlrev_b64 v[18:19], 16, v[18:19]
	v_lshlrev_b64 v[20:21], 16, v[20:21]
	v_lshl_add_u64 v[14:15], v[2:3], 0, v[14:15]
	v_lshl_add_u64 v[16:17], v[2:3], 0, v[16:17]
	global_load_dword v90, v[6:7], off
	global_load_dword v91, v[14:15], off
	global_load_dword v92, v[8:9], off
	global_load_dword v93, v[16:17], off
	v_lshl_add_u64 v[6:7], v[2:3], 0, v[10:11]
	v_lshlrev_b64 v[8:9], 16, v[34:35]
	v_lshl_add_u64 v[18:19], v[2:3], 0, v[18:19]
	v_lshl_add_u64 v[20:21], v[2:3], 0, v[20:21]
	v_lshl_add_u64 v[8:9], v[2:3], 0, v[8:9]
	global_load_dword v34, v[6:7], off
	global_load_dword v94, v[18:19], off
	global_load_dword v95, v[8:9], off
	global_load_dword v96, v[20:21], off
	v_or_b32_e32 v8, s11, v1
	v_or_b32_e32 v6, s16, v38
	s_add_i32 s9, s9, 16
	s_add_i32 s8, s8, 16
	s_add_i32 s10, s10, -16
	v_mad_u64_u32 v[6:7], s[26:27], v6, s21, v[44:45]
	v_mad_u64_u32 v[8:9], s[26:27], v8, s21, v[44:45]
	v_or_b32_e32 v7, s36, v1
	v_or_b32_e32 v9, s37, v38
	v_or_b32_e32 v16, s44, v1
	v_or_b32_e32 v14, s45, v38
	v_or_b32_e32 v20, s47, v1
	v_or_b32_e32 v18, s49, v38
	v_or_b32_e32 v24, s50, v1
	v_or_b32_e32 v22, s51, v38
	v_or_b32_e32 v28, s52, v1
	v_or_b32_e32 v26, s53, v38
	v_or_b32_e32 v32, s54, v1
	v_or_b32_e32 v30, s55, v38
	v_or_b32_e32 v82, s56, v1
	v_or_b32_e32 v80, s57, v38
	s_cmp_lg_u32 s10, 0
	v_mad_u64_u32 v[10:11], s[26:27], v9, s21, v[44:45]
	v_mad_u64_u32 v[12:13], s[26:27], v7, s21, v[44:45]
	v_mad_u64_u32 v[14:15], s[26:27], v14, s21, v[44:45]
	v_mad_u64_u32 v[16:17], s[26:27], v16, s21, v[44:45]
	v_mad_u64_u32 v[18:19], s[26:27], v18, s21, v[44:45]
	v_mad_u64_u32 v[20:21], s[26:27], v20, s21, v[44:45]
	v_mad_u64_u32 v[22:23], s[26:27], v22, s21, v[44:45]
	v_mad_u64_u32 v[24:25], s[26:27], v24, s21, v[44:45]
	v_mad_u64_u32 v[26:27], s[26:27], v26, s21, v[44:45]
	v_mad_u64_u32 v[28:29], s[26:27], v28, s21, v[44:45]
	v_mad_u64_u32 v[30:31], s[26:27], v30, s21, v[44:45]
	v_mad_u64_u32 v[32:33], s[26:27], v32, s21, v[44:45]
	v_mad_u64_u32 v[80:81], s[26:27], v80, s21, v[44:45]
	v_mad_u64_u32 v[82:83], s[26:27], v82, s21, v[44:45]
	s_waitcnt vmcnt(15)
	ds_write_b32 v6, v61
	s_waitcnt vmcnt(14)
	ds_write_b32 v8, v79
	s_waitcnt vmcnt(13)
	ds_write_b32 v10, v84
	s_waitcnt vmcnt(12)
	ds_write_b32 v12, v85
	s_waitcnt vmcnt(11)
	ds_write_b32 v14, v86
	s_waitcnt vmcnt(10)
	ds_write_b32 v16, v87
	s_waitcnt vmcnt(9)
	ds_write_b32 v18, v88
	s_waitcnt vmcnt(8)
	ds_write_b32 v20, v89
	s_waitcnt vmcnt(7)
	ds_write_b32 v22, v90
	s_waitcnt vmcnt(6)
	ds_write_b32 v24, v91
	s_waitcnt vmcnt(5)
	ds_write_b32 v26, v92
	s_waitcnt vmcnt(4)
	ds_write_b32 v28, v93
	s_waitcnt vmcnt(3)
	ds_write_b32 v30, v34
	s_waitcnt vmcnt(2)
	ds_write_b32 v32, v94
	s_waitcnt vmcnt(1)
	ds_write_b32 v80, v95
	s_waitcnt vmcnt(0)
	ds_write_b32 v82, v96
	s_cbranch_scc1 .LBB0_22
	s_waitcnt lgkmcnt(0)
	ds_read2_b32 v[2:3], v63 offset1:33
	v_add_u32_e32 v16, 0x800, v63
	v_add_u32_e32 v18, 0x400, v63
	v_add_u32_e32 v19, 0xc00, v63
	ds_read2_b32 v[4:5], v16 offset0:16 offset1:49
	ds_read2_b32 v[6:7], v63 offset0:66 offset1:99
	ds_read2_b32 v[8:9], v16 offset0:82 offset1:115
	ds_read2_b32 v[10:11], v63 offset0:132 offset1:165
	ds_read2_b32 v[12:13], v16 offset0:148 offset1:181
	ds_read2_b32 v[14:15], v63 offset0:198 offset1:231
	ds_read2_b32 v[16:17], v16 offset0:214 offset1:247
	ds_read2_b32 v[26:27], v18 offset0:8 offset1:41
	ds_read2_b32 v[28:29], v19 offset0:24 offset1:57
	ds_read2_b32 v[30:31], v18 offset0:74 offset1:107
	ds_read2_b32 v[32:33], v19 offset0:90 offset1:123
	ds_read2_b32 v[80:81], v18 offset0:140 offset1:173
	ds_read2_b32 v[82:83], v19 offset0:156 offset1:189
	ds_read2_b32 v[84:85], v18 offset0:206 offset1:239
	ds_read2_b32 v[86:87], v19 offset0:222 offset1:255
	s_waitcnt lgkmcnt(14)
	v_max_f32_e64 v18, |v4|, |v4|
	v_max_f32_e64 v19, |v2|, |v2|
	v_max_f32_e32 v18, v19, v18
	v_max_f32_e64 v19, |v5|, |v5|
	v_max_f32_e64 v20, |v3|, |v3|
	v_max_f32_e32 v19, v20, v19
	v_max3_f32 v18, v18, 0, v19
	s_waitcnt lgkmcnt(12)
	v_max_f32_e64 v19, |v8|, |v8|
	v_max_f32_e64 v20, |v6|, |v6|
	v_max_f32_e32 v19, v20, v19
	v_max_f32_e64 v20, |v9|, |v9|
	v_max_f32_e64 v21, |v7|, |v7|
	v_max_f32_e32 v20, v21, v20
	v_max3_f32 v18, v18, v19, v20
	s_waitcnt lgkmcnt(10)
	v_max_f32_e64 v19, |v12|, |v12|
	v_max_f32_e64 v20, |v10|, |v10|
	v_max_f32_e32 v19, v20, v19
	v_max_f32_e64 v20, |v13|, |v13|
	v_max_f32_e64 v21, |v11|, |v11|
	v_max_f32_e32 v20, v21, v20
	v_max3_f32 v18, v18, v19, v20
	s_waitcnt lgkmcnt(8)
	v_max_f32_e64 v19, |v16|, |v16|
	v_max_f32_e64 v20, |v14|, |v14|
	v_max_f32_e32 v19, v20, v19
	v_max_f32_e64 v20, |v17|, |v17|
	v_max_f32_e64 v21, |v15|, |v15|
	v_max_f32_e32 v20, v21, v20
	v_max3_f32 v18, v18, v19, v20
	s_waitcnt lgkmcnt(6)
	v_max_f32_e64 v19, |v28|, |v28|
	v_max_f32_e64 v20, |v26|, |v26|
	v_max_f32_e32 v19, v20, v19
	v_max_f32_e64 v20, |v29|, |v29|
	v_max_f32_e64 v21, |v27|, |v27|
	v_max_f32_e32 v20, v21, v20
	v_max3_f32 v18, v18, v19, v20
	s_waitcnt lgkmcnt(4)
	v_max_f32_e64 v19, |v32|, |v32|
	v_max_f32_e64 v20, |v30|, |v30|
	v_max_f32_e32 v19, v20, v19
	v_max_f32_e64 v20, |v33|, |v33|
	v_max_f32_e64 v21, |v31|, |v31|
	v_max_f32_e32 v20, v21, v20
	v_max3_f32 v18, v18, v19, v20
	s_waitcnt lgkmcnt(2)
	v_max_f32_e64 v19, |v82|, |v82|
	v_max_f32_e64 v20, |v80|, |v80|
	v_max_f32_e32 v19, v20, v19
	v_max_f32_e64 v20, |v83|, |v83|
	v_max_f32_e64 v21, |v81|, |v81|
	v_max_f32_e32 v20, v21, v20
	v_max3_f32 v18, v18, v19, v20
	s_waitcnt lgkmcnt(0)
	v_max_f32_e64 v19, |v86|, |v86|
	v_max_f32_e64 v20, |v84|, |v84|
	v_max_f32_e32 v19, v20, v19
	v_max_f32_e64 v20, |v87|, |v87|
	v_max_f32_e64 v21, |v85|, |v85|
	v_max_f32_e32 v20, v21, v20
	v_max3_f32 v18, v18, v19, v20
	v_bfe_u32 v18, v18, 23, 8
	v_max_u32_e32 v34, 3, v18
	v_lshlrev_b32_e32 v18, 23, v34
	v_sub_u32_e32 v61, 0x80000000, v18
	v_mul_f32_e32 v4, v4, v61
	v_med3_f32 v18, v4, s40, v78
	v_mul_f32_e32 v4, v5, v61
	v_mul_f32_e32 v5, v8, v61
	v_med3_f32 v19, v4, s40, v78
	v_mul_f32_e32 v4, v6, v61
	v_med3_f32 v20, v5, s40, v78
	v_mul_f32_e32 v5, v7, v61
	v_mul_f32_e32 v6, v9, v61
	v_mul_f32_e32 v7, v12, v61
	v_mul_f32_e32 v8, v13, v61
	v_mul_f32_e32 v9, v16, v61
	v_med3_f32 v21, v6, s40, v78
	v_mul_f32_e32 v6, v10, v61
	v_med3_f32 v22, v7, s40, v78
	v_mul_f32_e32 v7, v11, v61
	v_med3_f32 v23, v8, s40, v78
	v_mul_f32_e32 v8, v14, v61
	v_med3_f32 v24, v9, s40, v78
	v_mul_f32_e32 v9, v15, v61
	v_mul_f32_e32 v10, v17, v61
	v_mul_f32_e32 v11, v28, v61
	v_mul_f32_e32 v12, v29, v61
	v_mul_f32_e32 v13, v32, v61
	v_mul_f32_e32 v14, v33, v61
	v_mul_f32_e32 v15, v82, v61
	v_mul_f32_e32 v16, v83, v61
	v_mul_f32_e32 v17, v86, v61
	v_mul_f32_e32 v2, v2, v61
	v_mul_f32_e32 v3, v3, v61
	v_med3_f32 v25, v10, s40, v78
	v_mul_f32_e32 v10, v26, v61
	v_med3_f32 v26, v11, s40, v78
	v_mul_f32_e32 v11, v27, v61
	v_med3_f32 v27, v12, s40, v78
	v_mul_f32_e32 v12, v30, v61
	v_med3_f32 v28, v13, s40, v78
	v_mul_f32_e32 v13, v31, v61
	v_med3_f32 v29, v14, s40, v78
	v_mul_f32_e32 v14, v80, v61
	v_med3_f32 v30, v15, s40, v78
	v_mul_f32_e32 v15, v81, v61
	v_med3_f32 v31, v16, s40, v78
	v_mul_f32_e32 v16, v84, v61
	v_med3_f32 v32, v17, s40, v78
	v_mul_f32_e32 v17, v85, v61
	v_mul_f32_e32 v33, v87, v61
	v_med3_f32 v2, v2, s40, v78
	v_med3_f32 v3, v3, s40, v78
	v_med3_f32 v4, v4, s40, v78
	v_med3_f32 v5, v5, s40, v78
	v_med3_f32 v6, v6, s40, v78
	v_med3_f32 v7, v7, s40, v78
	v_med3_f32 v8, v8, s40, v78
	v_med3_f32 v9, v9, s40, v78
	v_med3_f32 v10, v10, s40, v78
	v_med3_f32 v11, v11, s40, v78
	v_med3_f32 v12, v12, s40, v78
	v_med3_f32 v13, v13, s40, v78
	v_med3_f32 v14, v14, s40, v78
	v_med3_f32 v15, v15, s40, v78
	v_med3_f32 v16, v16, s40, v78
	v_med3_f32 v17, v17, s40, v78
	v_med3_f32 v33, v33, s40, v78
	s_and_b32 s7, 0xffff, s7
	v_cvt_scalef32_2xpk16_fp6_f32 v[2:7], v[2:17], v[18:33], 1.0
	v_mov_b32_e32 v32, v6
	v_or_b32_e32 v6, s7, v40
	v_mov_b32_e32 v33, v7
	v_lshlrev_b32_e32 v6, 12, v6
	v_mov_b32_e32 v7, v35
	v_or_b32_e32 v8, s6, v41
	v_lshl_add_u64 v[6:7], s[18:19], 0, v[6:7]
	s_and_b32 s16, s6, 0x1f80
	v_lshrrev_b32_e32 v8, 1, v8
	v_and_b32_e32 v8, 48, v8
	v_mov_b32_e32 v9, v35
	v_lshl_add_u64 v[6:7], v[6:7], 0, s[16:17]
	v_lshl_add_u64 v[6:7], v[6:7], 0, v[8:9]
	v_add_u32_e32 v34, -2, v34
	global_store_dwordx4 v[6:7], v[2:5], off nt
	global_store_dwordx4 v[6:7], v[32:35], off offset:64 nt
	s_waitcnt lgkmcnt(0)

.LBB0_28:
	s_lshl_b32 s36, s16, 1
	s_lshl_b32 s37, s26, 1
	v_or_b32_e32 v34, s37, v4
	s_add_i32 s44, s36, 4
	s_add_i32 s45, s37, 4
	v_mov_b32_e32 v9, v35
	s_add_i32 s49, s37, 8
	v_lshlrev_b64 v[22:23], 14, v[34:35]
	v_or_b32_e32 v8, s44, v5
	v_or_b32_e32 v34, s45, v4
	v_mov_b32_e32 v7, v35
	v_or_b32_e32 v6, s36, v5
	s_add_i32 s51, s37, 12
	v_lshlrev_b64 v[8:9], 14, v[8:9]
	v_lshlrev_b64 v[24:25], 14, v[34:35]
	v_or_b32_e32 v34, s49, v4
	s_add_i32 s47, s36, 8
	s_add_i32 s50, s36, 12
	s_add_i32 s53, s37, 16
	v_lshlrev_b64 v[6:7], 14, v[6:7]
	v_lshl_add_u64 v[22:23], v[2:3], 0, v[22:23]
	v_lshl_add_u64 v[8:9], v[2:3], 0, v[8:9]
	v_lshlrev_b64 v[26:27], 14, v[34:35]
	v_or_b32_e32 v34, s51, v4
	v_mov_b32_e32 v11, v35
	v_mov_b32_e32 v13, v35
	s_add_i32 s55, s37, 20
	v_or_b32_e32 v10, s47, v5
	v_or_b32_e32 v12, s50, v5
	v_lshl_add_u64 v[6:7], v[2:3], 0, v[6:7]
	v_lshl_add_u64 v[24:25], v[2:3], 0, v[24:25]
	global_load_dword v61, v[22:23], off
	global_load_dword v79, v[6:7], off
	global_load_dword v84, v[24:25], off
	global_load_dword v85, v[8:9], off
	v_lshlrev_b64 v[8:9], 14, v[34:35]
	v_or_b32_e32 v34, s53, v4
	s_add_i32 s52, s36, 16
	s_add_i32 s54, s36, 20
	s_add_i32 s57, s37, 24
	v_lshlrev_b64 v[10:11], 14, v[10:11]
	v_lshlrev_b64 v[12:13], 14, v[12:13]
	v_lshl_add_u64 v[6:7], v[2:3], 0, v[26:27]
	v_lshl_add_u64 v[8:9], v[2:3], 0, v[8:9]
	v_lshlrev_b64 v[22:23], 14, v[34:35]
	v_or_b32_e32 v34, s55, v4
	v_mov_b32_e32 v15, v35
	v_mov_b32_e32 v17, v35
	s_add_i32 s56, s36, 24
	s_add_i32 s58, s36, 28
	s_add_i32 s59, s37, 28
	v_or_b32_e32 v14, s52, v5
	v_or_b32_e32 v16, s54, v5
	v_lshl_add_u64 v[10:11], v[2:3], 0, v[10:11]
	v_lshl_add_u64 v[12:13], v[2:3], 0, v[12:13]
	global_load_dword v86, v[6:7], off
	global_load_dword v87, v[10:11], off
	global_load_dword v88, v[8:9], off
	global_load_dword v89, v[12:13], off
	v_lshlrev_b64 v[8:9], 14, v[34:35]
	v_or_b32_e32 v34, s57, v4
	v_mov_b32_e32 v19, v35
	v_mov_b32_e32 v21, v35
	v_or_b32_e32 v18, s56, v5
	v_or_b32_e32 v20, s58, v5
	v_lshlrev_b64 v[14:15], 14, v[14:15]
	v_lshlrev_b64 v[16:17], 14, v[16:17]
	v_lshl_add_u64 v[6:7], v[2:3], 0, v[22:23]
	v_lshl_add_u64 v[8:9], v[2:3], 0, v[8:9]
	v_lshlrev_b64 v[10:11], 14, v[34:35]
	v_or_b32_e32 v34, s59, v4
	v_lshlrev_b64 v[18:19], 14, v[18:19]
	v_lshlrev_b64 v[20:21], 14, v[20:21]
	v_lshl_add_u64 v[14:15], v[2:3], 0, v[14:15]
	v_lshl_add_u64 v[16:17], v[2:3], 0, v[16:17]
	global_load_dword v90, v[6:7], off
	global_load_dword v91, v[14:15], off
	global_load_dword v92, v[8:9], off
	global_load_dword v93, v[16:17], off
	v_lshl_add_u64 v[6:7], v[2:3], 0, v[10:11]
	v_lshlrev_b64 v[8:9], 14, v[34:35]
	v_lshl_add_u64 v[18:19], v[2:3], 0, v[18:19]
	v_lshl_add_u64 v[20:21], v[2:3], 0, v[20:21]
	v_lshl_add_u64 v[8:9], v[2:3], 0, v[8:9]
	global_load_dword v34, v[6:7], off
	global_load_dword v94, v[18:19], off
	global_load_dword v95, v[8:9], off
	global_load_dword v96, v[20:21], off
	v_or_b32_e32 v8, s36, v1
	v_or_b32_e32 v6, s37, v38
	s_add_i32 s26, s26, 16
	s_add_i32 s16, s16, 16
	s_add_i32 s27, s27, -16
	v_mad_u64_u32 v[6:7], s[36:37], v6, s21, v[44:45]
	v_mad_u64_u32 v[8:9], s[36:37], v8, s21, v[44:45]
	v_or_b32_e32 v7, s44, v1
	v_or_b32_e32 v9, s45, v38
	v_or_b32_e32 v16, s47, v1
	v_or_b32_e32 v14, s49, v38
	v_or_b32_e32 v20, s50, v1
	v_or_b32_e32 v18, s51, v38
	v_or_b32_e32 v24, s52, v1
	v_or_b32_e32 v22, s53, v38
	v_or_b32_e32 v28, s54, v1
	v_or_b32_e32 v26, s55, v38
	v_or_b32_e32 v32, s56, v1
	v_or_b32_e32 v30, s57, v38
	v_or_b32_e32 v82, s58, v1
	v_or_b32_e32 v80, s59, v38
	s_cmp_lg_u32 s27, 0
	v_mad_u64_u32 v[10:11], s[36:37], v9, s21, v[44:45]
	v_mad_u64_u32 v[12:13], s[36:37], v7, s21, v[44:45]
	v_mad_u64_u32 v[14:15], s[36:37], v14, s21, v[44:45]
	v_mad_u64_u32 v[16:17], s[36:37], v16, s21, v[44:45]
	v_mad_u64_u32 v[18:19], s[36:37], v18, s21, v[44:45]
	v_mad_u64_u32 v[20:21], s[36:37], v20, s21, v[44:45]
	v_mad_u64_u32 v[22:23], s[36:37], v22, s21, v[44:45]
	v_mad_u64_u32 v[24:25], s[36:37], v24, s21, v[44:45]
	v_mad_u64_u32 v[26:27], s[36:37], v26, s21, v[44:45]
	v_mad_u64_u32 v[28:29], s[36:37], v28, s21, v[44:45]
	v_mad_u64_u32 v[30:31], s[36:37], v30, s21, v[44:45]
	v_mad_u64_u32 v[32:33], s[36:37], v32, s21, v[44:45]
	v_mad_u64_u32 v[80:81], s[36:37], v80, s21, v[44:45]
	v_mad_u64_u32 v[82:83], s[36:37], v82, s21, v[44:45]
	s_waitcnt vmcnt(15)
	ds_write_b32 v6, v61
	s_waitcnt vmcnt(14)
	ds_write_b32 v8, v79
	s_waitcnt vmcnt(13)
	ds_write_b32 v10, v84
	s_waitcnt vmcnt(12)
	ds_write_b32 v12, v85
	s_waitcnt vmcnt(11)
	ds_write_b32 v14, v86
	s_waitcnt vmcnt(10)
	ds_write_b32 v16, v87
	s_waitcnt vmcnt(9)
	ds_write_b32 v18, v88
	s_waitcnt vmcnt(8)
	ds_write_b32 v20, v89
	s_waitcnt vmcnt(7)
	ds_write_b32 v22, v90
	s_waitcnt vmcnt(6)
	ds_write_b32 v24, v91
	s_waitcnt vmcnt(5)
	ds_write_b32 v26, v92
	s_waitcnt vmcnt(4)
	ds_write_b32 v28, v93
	s_waitcnt vmcnt(3)
	ds_write_b32 v30, v34
	s_waitcnt vmcnt(2)
	ds_write_b32 v32, v94
	s_waitcnt vmcnt(1)
	ds_write_b32 v80, v95
	s_waitcnt vmcnt(0)
	ds_write_b32 v82, v96
	s_cbranch_scc1 .LBB0_28
	s_waitcnt lgkmcnt(0)
	ds_read2_b32 v[2:3], v63 offset1:33
	v_add_u32_e32 v16, 0x800, v63
	v_add_u32_e32 v18, 0x400, v63
	v_add_u32_e32 v19, 0xc00, v63
	ds_read2_b32 v[4:5], v16 offset0:16 offset1:49
	ds_read2_b32 v[6:7], v63 offset0:66 offset1:99
	ds_read2_b32 v[8:9], v16 offset0:82 offset1:115
	ds_read2_b32 v[10:11], v63 offset0:132 offset1:165
	ds_read2_b32 v[12:13], v16 offset0:148 offset1:181
	ds_read2_b32 v[14:15], v63 offset0:198 offset1:231
	ds_read2_b32 v[16:17], v16 offset0:214 offset1:247
	ds_read2_b32 v[26:27], v18 offset0:8 offset1:41
	ds_read2_b32 v[28:29], v19 offset0:24 offset1:57
	ds_read2_b32 v[30:31], v18 offset0:74 offset1:107
	ds_read2_b32 v[32:33], v19 offset0:90 offset1:123
	ds_read2_b32 v[80:81], v18 offset0:140 offset1:173
	ds_read2_b32 v[82:83], v19 offset0:156 offset1:189
	ds_read2_b32 v[84:85], v18 offset0:206 offset1:239
	ds_read2_b32 v[86:87], v19 offset0:222 offset1:255
	s_waitcnt lgkmcnt(14)
	v_max_f32_e64 v18, |v4|, |v4|
	v_max_f32_e64 v19, |v2|, |v2|
	v_max_f32_e32 v18, v19, v18
	v_max_f32_e64 v19, |v5|, |v5|
	v_max_f32_e64 v20, |v3|, |v3|
	v_max_f32_e32 v19, v20, v19
	v_max3_f32 v18, v18, 0, v19
	s_waitcnt lgkmcnt(12)
	v_max_f32_e64 v19, |v8|, |v8|
	v_max_f32_e64 v20, |v6|, |v6|
	v_max_f32_e32 v19, v20, v19
	v_max_f32_e64 v20, |v9|, |v9|
	v_max_f32_e64 v21, |v7|, |v7|
	v_max_f32_e32 v20, v21, v20
	v_max3_f32 v18, v18, v19, v20
	s_waitcnt lgkmcnt(10)
	v_max_f32_e64 v19, |v12|, |v12|
	v_max_f32_e64 v20, |v10|, |v10|
	v_max_f32_e32 v19, v20, v19
	v_max_f32_e64 v20, |v13|, |v13|
	v_max_f32_e64 v21, |v11|, |v11|
	v_max_f32_e32 v20, v21, v20
	v_max3_f32 v18, v18, v19, v20
	s_waitcnt lgkmcnt(8)
	v_max_f32_e64 v19, |v16|, |v16|
	v_max_f32_e64 v20, |v14|, |v14|
	v_max_f32_e32 v19, v20, v19
	v_max_f32_e64 v20, |v17|, |v17|
	v_max_f32_e64 v21, |v15|, |v15|
	v_max_f32_e32 v20, v21, v20
	v_max3_f32 v18, v18, v19, v20
	s_waitcnt lgkmcnt(6)
	v_max_f32_e64 v19, |v28|, |v28|
	v_max_f32_e64 v20, |v26|, |v26|
	v_max_f32_e32 v19, v20, v19
	v_max_f32_e64 v20, |v29|, |v29|
	v_max_f32_e64 v21, |v27|, |v27|
	v_max_f32_e32 v20, v21, v20
	v_max3_f32 v18, v18, v19, v20
	s_waitcnt lgkmcnt(4)
	v_max_f32_e64 v19, |v32|, |v32|
	v_max_f32_e64 v20, |v30|, |v30|
	v_max_f32_e32 v19, v20, v19
	v_max_f32_e64 v20, |v33|, |v33|
	v_max_f32_e64 v21, |v31|, |v31|
	v_max_f32_e32 v20, v21, v20
	v_max3_f32 v18, v18, v19, v20
	s_waitcnt lgkmcnt(2)
	v_max_f32_e64 v19, |v82|, |v82|
	v_max_f32_e64 v20, |v80|, |v80|
	v_max_f32_e32 v19, v20, v19
	v_max_f32_e64 v20, |v83|, |v83|
	v_max_f32_e64 v21, |v81|, |v81|
	v_max_f32_e32 v20, v21, v20
	v_max3_f32 v18, v18, v19, v20
	s_waitcnt lgkmcnt(0)
	v_max_f32_e64 v19, |v86|, |v86|
	v_max_f32_e64 v20, |v84|, |v84|
	v_max_f32_e32 v19, v20, v19
	v_max_f32_e64 v20, |v87|, |v87|
	v_max_f32_e64 v21, |v85|, |v85|
	v_max_f32_e32 v20, v21, v20
	v_max3_f32 v18, v18, v19, v20
	v_bfe_u32 v18, v18, 23, 8
	v_max_u32_e32 v34, 3, v18
	v_lshlrev_b32_e32 v18, 23, v34
	v_sub_u32_e32 v61, 0x80000000, v18
	v_mul_f32_e32 v4, v4, v61
	v_med3_f32 v18, v4, s40, v78
	v_mul_f32_e32 v4, v5, v61
	v_mul_f32_e32 v5, v8, v61
	v_med3_f32 v19, v4, s40, v78
	v_mul_f32_e32 v4, v6, v61
	v_med3_f32 v20, v5, s40, v78
	v_mul_f32_e32 v5, v7, v61
	v_mul_f32_e32 v6, v9, v61
	v_mul_f32_e32 v7, v12, v61
	v_mul_f32_e32 v8, v13, v61
	v_mul_f32_e32 v9, v16, v61
	v_med3_f32 v21, v6, s40, v78
	v_mul_f32_e32 v6, v10, v61
	v_med3_f32 v22, v7, s40, v78
	v_mul_f32_e32 v7, v11, v61
	v_med3_f32 v23, v8, s40, v78
	v_mul_f32_e32 v8, v14, v61
	v_med3_f32 v24, v9, s40, v78
	v_mul_f32_e32 v9, v15, v61
	v_mul_f32_e32 v10, v17, v61
	v_mul_f32_e32 v11, v28, v61
	v_mul_f32_e32 v12, v29, v61
	v_mul_f32_e32 v13, v32, v61
	v_mul_f32_e32 v14, v33, v61
	v_mul_f32_e32 v15, v82, v61
	v_mul_f32_e32 v16, v83, v61
	v_mul_f32_e32 v17, v86, v61
	v_mul_f32_e32 v2, v2, v61
	v_mul_f32_e32 v3, v3, v61
	v_med3_f32 v25, v10, s40, v78
	v_mul_f32_e32 v10, v26, v61
	v_med3_f32 v26, v11, s40, v78
	v_mul_f32_e32 v11, v27, v61
	v_med3_f32 v27, v12, s40, v78
	v_mul_f32_e32 v12, v30, v61
	v_med3_f32 v28, v13, s40, v78
	v_mul_f32_e32 v13, v31, v61
	v_med3_f32 v29, v14, s40, v78
	v_mul_f32_e32 v14, v80, v61
	v_med3_f32 v30, v15, s40, v78
	v_mul_f32_e32 v15, v81, v61
	v_med3_f32 v31, v16, s40, v78
	v_mul_f32_e32 v16, v84, v61
	v_med3_f32 v32, v17, s40, v78
	v_mul_f32_e32 v17, v85, v61
	v_mul_f32_e32 v33, v87, v61
	v_med3_f32 v2, v2, s40, v78
	v_med3_f32 v3, v3, s40, v78
	v_med3_f32 v4, v4, s40, v78
	v_med3_f32 v5, v5, s40, v78
	v_med3_f32 v6, v6, s40, v78
	v_med3_f32 v7, v7, s40, v78
	v_med3_f32 v8, v8, s40, v78
	v_med3_f32 v9, v9, s40, v78
	v_med3_f32 v10, v10, s40, v78
	v_med3_f32 v11, v11, s40, v78
	v_med3_f32 v12, v12, s40, v78
	v_med3_f32 v13, v13, s40, v78
	v_med3_f32 v14, v14, s40, v78
	v_med3_f32 v15, v15, s40, v78
	v_med3_f32 v16, v16, s40, v78
	v_med3_f32 v17, v17, s40, v78
	v_med3_f32 v33, v33, s40, v78
	s_and_b32 s11, 0xffff, s11
	v_cvt_scalef32_2xpk16_fp6_f32 v[2:7], v[2:17], v[18:33], 1.0
	v_mov_b32_e32 v32, v6
	v_or_b32_e32 v6, s11, v40
	v_mov_b32_e32 v33, v7
	v_mul_u32_u24_e32 v6, 0x1800, v6
	v_mov_b32_e32 v7, v35
	v_or_b32_e32 v8, s9, v41
	v_lshl_add_u64 v[6:7], s[14:15], 0, v[6:7]
	s_and_b32 s16, s8, 0x7f80
	v_lshrrev_b32_e32 v8, 1, v8
	v_and_b32_e32 v8, 48, v8
	v_mov_b32_e32 v9, v35
	v_lshl_add_u64 v[6:7], v[6:7], 0, s[16:17]
	v_lshl_add_u64 v[6:7], v[6:7], 0, v[8:9]
	v_lshl_add_u64 v[8:9], v[6:7], 0, s[22:23]
	v_add_co_u32_e32 v6, vcc, 0x800000, v6
	v_add_u32_e32 v34, -2, v34
	s_nop 0
	v_addc_co_u32_e32 v7, vcc, 0, v7, vcc
	global_store_dwordx4 v[6:7], v[2:5], off offset:2048 nt
	global_store_dwordx4 v[8:9], v[32:35], off offset:64 nt
	s_waitcnt lgkmcnt(0)
	s_mov_b64 s[8:9], 0

.LBB0_32:
	s_lshl_b32 s10, s11, 1
	s_lshl_b32 s16, s6, 1
	v_or_b32_e32 v34, s16, v4
	s_add_i32 s36, s10, 4
	s_add_i32 s37, s16, 4
	v_mov_b32_e32 v9, v35
	s_add_i32 s45, s16, 8
	v_lshlrev_b64 v[22:23], 14, v[34:35]
	v_or_b32_e32 v8, s36, v5
	v_or_b32_e32 v34, s37, v4
	v_mov_b32_e32 v7, v35
	v_or_b32_e32 v6, s10, v5
	s_add_i32 s49, s16, 12
	v_lshlrev_b64 v[8:9], 14, v[8:9]
	v_lshlrev_b64 v[24:25], 14, v[34:35]
	v_or_b32_e32 v34, s45, v4
	s_add_i32 s44, s10, 8
	s_add_i32 s47, s10, 12
	s_add_i32 s51, s16, 16
	v_lshlrev_b64 v[6:7], 14, v[6:7]
	v_lshl_add_u64 v[22:23], v[2:3], 0, v[22:23]
	v_lshl_add_u64 v[8:9], v[2:3], 0, v[8:9]
	v_lshlrev_b64 v[26:27], 14, v[34:35]
	v_or_b32_e32 v34, s49, v4
	v_mov_b32_e32 v11, v35
	v_mov_b32_e32 v13, v35
	s_add_i32 s53, s16, 20
	v_or_b32_e32 v10, s44, v5
	v_or_b32_e32 v12, s47, v5
	v_lshl_add_u64 v[6:7], v[2:3], 0, v[6:7]
	v_lshl_add_u64 v[24:25], v[2:3], 0, v[24:25]
	global_load_dword v61, v[22:23], off
	global_load_dword v79, v[6:7], off
	global_load_dword v84, v[24:25], off
	global_load_dword v85, v[8:9], off
	v_lshlrev_b64 v[8:9], 14, v[34:35]
	v_or_b32_e32 v34, s51, v4
	s_add_i32 s50, s10, 16
	s_add_i32 s52, s10, 20
	s_add_i32 s55, s16, 24
	v_lshlrev_b64 v[10:11], 14, v[10:11]
	v_lshlrev_b64 v[12:13], 14, v[12:13]
	v_lshl_add_u64 v[6:7], v[2:3], 0, v[26:27]
	v_lshl_add_u64 v[8:9], v[2:3], 0, v[8:9]
	v_lshlrev_b64 v[22:23], 14, v[34:35]
	v_or_b32_e32 v34, s53, v4
	v_mov_b32_e32 v15, v35
	v_mov_b32_e32 v17, v35
	s_add_i32 s54, s10, 24
	s_add_i32 s56, s10, 28
	s_add_i32 s57, s16, 28
	v_or_b32_e32 v14, s50, v5
	v_or_b32_e32 v16, s52, v5
	v_lshl_add_u64 v[10:11], v[2:3], 0, v[10:11]
	v_lshl_add_u64 v[12:13], v[2:3], 0, v[12:13]
	global_load_dword v86, v[6:7], off
	global_load_dword v87, v[10:11], off
	global_load_dword v88, v[8:9], off
	global_load_dword v89, v[12:13], off
	v_lshlrev_b64 v[8:9], 14, v[34:35]
	v_or_b32_e32 v34, s55, v4
	v_mov_b32_e32 v19, v35
	v_mov_b32_e32 v21, v35
	v_or_b32_e32 v18, s54, v5
	v_or_b32_e32 v20, s56, v5
	v_lshlrev_b64 v[14:15], 14, v[14:15]
	v_lshlrev_b64 v[16:17], 14, v[16:17]
	v_lshl_add_u64 v[6:7], v[2:3], 0, v[22:23]
	v_lshl_add_u64 v[8:9], v[2:3], 0, v[8:9]
	v_lshlrev_b64 v[10:11], 14, v[34:35]
	v_or_b32_e32 v34, s57, v4
	v_lshlrev_b64 v[18:19], 14, v[18:19]
	v_lshlrev_b64 v[20:21], 14, v[20:21]
	v_lshl_add_u64 v[14:15], v[2:3], 0, v[14:15]
	v_lshl_add_u64 v[16:17], v[2:3], 0, v[16:17]
	global_load_dword v90, v[6:7], off
	global_load_dword v91, v[14:15], off
	global_load_dword v92, v[8:9], off
	global_load_dword v93, v[16:17], off
	v_lshl_add_u64 v[6:7], v[2:3], 0, v[10:11]
	v_lshlrev_b64 v[8:9], 14, v[34:35]
	v_lshl_add_u64 v[18:19], v[2:3], 0, v[18:19]
	v_lshl_add_u64 v[20:21], v[2:3], 0, v[20:21]
	v_lshl_add_u64 v[8:9], v[2:3], 0, v[8:9]
	global_load_dword v34, v[6:7], off
	global_load_dword v94, v[18:19], off
	global_load_dword v95, v[8:9], off
	global_load_dword v96, v[20:21], off
	v_or_b32_e32 v8, s10, v1
	v_or_b32_e32 v6, s16, v38
	s_add_i32 s6, s6, 16
	s_add_i32 s11, s11, 16
	s_add_i32 s7, s7, -16
	v_mad_u64_u32 v[6:7], s[26:27], v6, s21, v[44:45]
	v_mad_u64_u32 v[8:9], s[26:27], v8, s21, v[44:45]
	v_or_b32_e32 v7, s36, v1
	v_or_b32_e32 v9, s37, v38
	v_or_b32_e32 v16, s44, v1
	v_or_b32_e32 v14, s45, v38
	v_or_b32_e32 v20, s47, v1
	v_or_b32_e32 v18, s49, v38
	v_or_b32_e32 v24, s50, v1
	v_or_b32_e32 v22, s51, v38
	v_or_b32_e32 v28, s52, v1
	v_or_b32_e32 v26, s53, v38
	v_or_b32_e32 v32, s54, v1
	v_or_b32_e32 v30, s55, v38
	v_or_b32_e32 v82, s56, v1
	v_or_b32_e32 v80, s57, v38
	s_cmp_lg_u32 s7, 0
	v_mad_u64_u32 v[10:11], s[26:27], v9, s21, v[44:45]
	v_mad_u64_u32 v[12:13], s[26:27], v7, s21, v[44:45]
	v_mad_u64_u32 v[14:15], s[26:27], v14, s21, v[44:45]
	v_mad_u64_u32 v[16:17], s[26:27], v16, s21, v[44:45]
	v_mad_u64_u32 v[18:19], s[26:27], v18, s21, v[44:45]
	v_mad_u64_u32 v[20:21], s[26:27], v20, s21, v[44:45]
	v_mad_u64_u32 v[22:23], s[26:27], v22, s21, v[44:45]
	v_mad_u64_u32 v[24:25], s[26:27], v24, s21, v[44:45]
	v_mad_u64_u32 v[26:27], s[26:27], v26, s21, v[44:45]
	v_mad_u64_u32 v[28:29], s[26:27], v28, s21, v[44:45]
	v_mad_u64_u32 v[30:31], s[26:27], v30, s21, v[44:45]
	v_mad_u64_u32 v[32:33], s[26:27], v32, s21, v[44:45]
	v_mad_u64_u32 v[80:81], s[26:27], v80, s21, v[44:45]
	v_mad_u64_u32 v[82:83], s[26:27], v82, s21, v[44:45]
	s_waitcnt vmcnt(15)
	ds_write_b32 v6, v61
	s_waitcnt vmcnt(14)
	ds_write_b32 v8, v79
	s_waitcnt vmcnt(13)
	ds_write_b32 v10, v84
	s_waitcnt vmcnt(12)
	ds_write_b32 v12, v85
	s_waitcnt vmcnt(11)
	ds_write_b32 v14, v86
	s_waitcnt vmcnt(10)
	ds_write_b32 v16, v87
	s_waitcnt vmcnt(9)
	ds_write_b32 v18, v88
	s_waitcnt vmcnt(8)
	ds_write_b32 v20, v89
	s_waitcnt vmcnt(7)
	ds_write_b32 v22, v90
	s_waitcnt vmcnt(6)
	ds_write_b32 v24, v91
	s_waitcnt vmcnt(5)
	ds_write_b32 v26, v92
	s_waitcnt vmcnt(4)
	ds_write_b32 v28, v93
	s_waitcnt vmcnt(3)
	ds_write_b32 v30, v34
	s_waitcnt vmcnt(2)
	ds_write_b32 v32, v94
	s_waitcnt vmcnt(1)
	ds_write_b32 v80, v95
	s_waitcnt vmcnt(0)
	ds_write_b32 v82, v96
	s_cbranch_scc1 .LBB0_32
	s_waitcnt lgkmcnt(0)
	ds_read2_b32 v[6:7], v65 offset1:8
	ds_read2_b32 v[10:11], v65 offset0:33 offset1:41
	ds_read2_b32 v[12:13], v65 offset0:66 offset1:74
	ds_read2_b32 v[14:15], v65 offset0:99 offset1:107
	ds_read2_b32 v[16:17], v65 offset0:132 offset1:140
	ds_read2_b32 v[18:19], v65 offset0:165 offset1:173
	s_waitcnt lgkmcnt(5)
	v_bfe_u32 v2, v6, 16, 1
	v_add3_u32 v2, v6, v2, s41
	s_waitcnt lgkmcnt(4)
	v_bfe_u32 v3, v10, 16, 1
	v_lshrrev_b32_e32 v2, 16, v2
	v_add3_u32 v3, v10, v3, s41
	v_and_or_b32 v2, v3, s42, v2
	s_waitcnt lgkmcnt(3)
	v_bfe_u32 v3, v12, 16, 1
	v_add3_u32 v3, v12, v3, s41
	s_waitcnt lgkmcnt(2)
	v_bfe_u32 v4, v14, 16, 1
	ds_read2_b32 v[20:21], v65 offset0:198 offset1:206
	v_lshrrev_b32_e32 v3, 16, v3
	v_add3_u32 v4, v14, v4, s41
	ds_read2_b32 v[22:23], v65 offset0:231 offset1:239
	v_and_or_b32 v3, v4, s42, v3
	s_waitcnt lgkmcnt(3)
	v_bfe_u32 v4, v16, 16, 1
	v_add3_u32 v4, v16, v4, s41
	s_waitcnt lgkmcnt(2)
	v_bfe_u32 v5, v18, 16, 1
	v_lshrrev_b32_e32 v4, 16, v4
	v_add3_u32 v5, v18, v5, s41
	v_and_or_b32 v4, v5, s42, v4
	s_waitcnt lgkmcnt(1)
	v_bfe_u32 v5, v20, 16, 1
	v_add3_u32 v5, v20, v5, s41
	s_waitcnt lgkmcnt(0)
	v_bfe_u32 v6, v22, 16, 1
	v_lshrrev_b32_e32 v5, 16, v5
	v_add3_u32 v6, v22, v6, s41
	v_and_or_b32 v5, v6, s42, v5
	v_or_b32_e32 v6, s8, v64
	s_lshl_b32 s16, s9, 1
	v_mul_u32_u24_e32 v6, 0xc00, v6
	v_lshl_add_u64 v[8:9], v[48:49], 0, s[16:17]
	v_lshlrev_b32_e32 v34, 1, v6
	v_lshl_add_u64 v[24:25], v[8:9], 0, v[34:35]
	global_store_dwordx4 v[24:25], v[2:5], off nt
	v_bfe_u32 v6, v23, 16, 1
	v_add3_u32 v6, v23, v6, s41
	v_bfe_u32 v2, v7, 16, 1
	v_add3_u32 v2, v7, v2, s41
	v_bfe_u32 v3, v11, 16, 1
	v_lshrrev_b32_e32 v2, 16, v2
	v_add3_u32 v3, v11, v3, s41
	v_and_or_b32 v2, v3, s42, v2
	v_bfe_u32 v3, v13, 16, 1
	v_add3_u32 v3, v13, v3, s41
	v_bfe_u32 v4, v15, 16, 1
	v_lshrrev_b32_e32 v3, 16, v3
	v_add3_u32 v4, v15, v4, s41
	v_and_or_b32 v3, v4, s42, v3
	v_bfe_u32 v4, v17, 16, 1
	v_add3_u32 v4, v17, v4, s41
	v_bfe_u32 v5, v19, 16, 1
	v_lshrrev_b32_e32 v4, 16, v4
	v_add3_u32 v5, v19, v5, s41
	v_and_or_b32 v4, v5, s42, v4
	v_bfe_u32 v5, v21, 16, 1
	v_add3_u32 v5, v21, v5, s41
	v_lshrrev_b32_e32 v5, 16, v5
	v_and_or_b32 v5, v6, s42, v5
	v_or_b32_e32 v6, s8, v66
	v_mul_u32_u24_e32 v10, 0xc00, v6
	v_lshlrev_b32_e32 v34, 1, v10
	ds_read2_b32 v[6:7], v65 offset0:16 offset1:24
	v_lshl_add_u64 v[10:11], v[8:9], 0, v[34:35]
	global_store_dwordx4 v[10:11], v[2:5], off nt
	ds_read2_b32 v[10:11], v65 offset0:49 offset1:57
	ds_read2_b32 v[12:13], v65 offset0:82 offset1:90
	ds_read2_b32 v[14:15], v65 offset0:115 offset1:123
	s_waitcnt lgkmcnt(3)
	v_bfe_u32 v2, v6, 16, 1
	v_add3_u32 v2, v6, v2, s41
	s_waitcnt lgkmcnt(2)
	v_bfe_u32 v3, v10, 16, 1
	ds_read2_b32 v[16:17], v65 offset0:148 offset1:156
	v_lshrrev_b32_e32 v2, 16, v2
	v_add3_u32 v3, v10, v3, s41
	ds_read2_b32 v[18:19], v65 offset0:181 offset1:189
	v_and_or_b32 v2, v3, s42, v2
	s_waitcnt lgkmcnt(3)
	v_bfe_u32 v3, v12, 16, 1
	v_add3_u32 v3, v12, v3, s41
	s_waitcnt lgkmcnt(2)
	v_bfe_u32 v4, v14, 16, 1
	ds_read2_b32 v[20:21], v65 offset0:214 offset1:222
	v_lshrrev_b32_e32 v3, 16, v3
	v_add3_u32 v4, v14, v4, s41
	ds_read2_b32 v[22:23], v65 offset0:247 offset1:255
	v_and_or_b32 v3, v4, s42, v3
	s_waitcnt lgkmcnt(3)
	v_bfe_u32 v4, v16, 16, 1
	v_add3_u32 v4, v16, v4, s41
	s_waitcnt lgkmcnt(2)
	v_bfe_u32 v5, v18, 16, 1
	v_lshrrev_b32_e32 v4, 16, v4
	v_add3_u32 v5, v18, v5, s41
	v_and_or_b32 v4, v5, s42, v4
	s_waitcnt lgkmcnt(1)
	v_bfe_u32 v5, v20, 16, 1
	v_add3_u32 v5, v20, v5, s41
	s_waitcnt lgkmcnt(0)
	v_bfe_u32 v6, v22, 16, 1
	v_lshrrev_b32_e32 v5, 16, v5
	v_add3_u32 v6, v22, v6, s41
	v_and_or_b32 v5, v6, s42, v5
	v_or_b32_e32 v6, s8, v67
	v_mul_u32_u24_e32 v6, 0xc00, v6
	v_lshlrev_b32_e32 v34, 1, v6
	v_lshl_add_u64 v[24:25], v[8:9], 0, v[34:35]
	global_store_dwordx4 v[24:25], v[2:5], off nt
	v_bfe_u32 v6, v23, 16, 1
	v_add3_u32 v6, v23, v6, s41
	v_bfe_u32 v2, v7, 16, 1
	v_add3_u32 v2, v7, v2, s41
	v_bfe_u32 v3, v11, 16, 1
	v_lshrrev_b32_e32 v2, 16, v2
	v_add3_u32 v3, v11, v3, s41
	v_and_or_b32 v2, v3, s42, v2
	v_bfe_u32 v3, v13, 16, 1
	v_add3_u32 v3, v13, v3, s41
	v_bfe_u32 v4, v15, 16, 1
	v_lshrrev_b32_e32 v3, 16, v3
	v_add3_u32 v4, v15, v4, s41
	v_and_or_b32 v3, v4, s42, v3
	v_bfe_u32 v4, v17, 16, 1
	v_add3_u32 v4, v17, v4, s41
	v_bfe_u32 v5, v19, 16, 1
	v_lshrrev_b32_e32 v4, 16, v4
	v_add3_u32 v5, v19, v5, s41
	v_and_or_b32 v4, v5, s42, v4
	v_bfe_u32 v5, v21, 16, 1
	v_add3_u32 v5, v21, v5, s41
	v_lshrrev_b32_e32 v5, 16, v5
	v_and_or_b32 v5, v6, s42, v5
	v_or_b32_e32 v6, s8, v68
	v_mul_u32_u24_e32 v6, 0xc00, v6
	v_lshlrev_b32_e32 v34, 1, v6
	v_lshl_add_u64 v[6:7], v[8:9], 0, v[34:35]
	global_store_dwordx4 v[6:7], v[2:5], off nt
	s_waitcnt lgkmcnt(0)

.LBB0_54:
	s_waitcnt lgkmcnt(0)
	ds_read2_b32 v[6:7], v59 offset1:16
	ds_read2_b32 v[8:9], v59 offset0:33 offset1:49
	ds_read2_b32 v[10:11], v59 offset0:66 offset1:82
	ds_read2_b32 v[12:13], v59 offset0:99 offset1:115
	ds_read2_b32 v[16:17], v59 offset0:132 offset1:148
	ds_read2_b32 v[18:19], v59 offset0:165 offset1:181
	ds_read2_b32 v[20:21], v59 offset0:198 offset1:214
	ds_read2_b32 v[22:23], v59 offset0:231 offset1:247
	s_waitcnt lgkmcnt(7)
	v_max_f32_e32 v2, v6, v6
	s_waitcnt lgkmcnt(6)
	v_max_f32_e32 v3, v8, v8
	v_med3_f32 v6, v2, s39, v77
	v_med3_f32 v3, v3, s39, v77
	v_mov_b32_e32 v2, v35
	v_cvt_pk_fp8_f32 v2, v6, v3
	s_waitcnt lgkmcnt(5)
	v_max_f32_e32 v4, v10, v10
	s_waitcnt lgkmcnt(4)
	v_max_f32_e32 v5, v12, v12
	v_med3_f32 v4, v4, s39, v77
	v_med3_f32 v5, v5, s39, v77
	v_cvt_pk_fp8_f32 v2, v4, v5 op_sel:[0,0,1]
	s_waitcnt lgkmcnt(3)
	v_max_f32_e32 v3, v16, v16
	s_waitcnt lgkmcnt(2)
	v_max_f32_e32 v4, v18, v18
	v_med3_f32 v8, v3, s39, v77
	v_med3_f32 v4, v4, s39, v77
	v_mov_b32_e32 v3, v35
	v_cvt_pk_fp8_f32 v3, v8, v4
	v_add_u32_e32 v8, 0x400, v59
	ds_read2_b32 v[24:25], v8 offset0:8 offset1:24
	ds_read2_b32 v[26:27], v8 offset0:41 offset1:57
	ds_read2_b32 v[28:29], v8 offset0:74 offset1:90
	ds_read2_b32 v[30:31], v8 offset0:107 offset1:123
	s_waitcnt lgkmcnt(5)
	v_max_f32_e32 v5, v20, v20
	s_waitcnt lgkmcnt(4)
	v_max_f32_e32 v6, v22, v22
	v_med3_f32 v5, v5, s39, v77
	v_med3_f32 v6, v6, s39, v77
	v_cvt_pk_fp8_f32 v3, v5, v6 op_sel:[0,0,1]
	s_waitcnt lgkmcnt(3)
	v_max_f32_e32 v4, v24, v24
	s_waitcnt lgkmcnt(2)
	v_max_f32_e32 v5, v26, v26
	v_med3_f32 v12, v4, s39, v77
	v_med3_f32 v5, v5, s39, v77
	v_mov_b32_e32 v4, v35
	v_cvt_pk_fp8_f32 v4, v12, v5
	ds_read2_b32 v[32:33], v8 offset0:140 offset1:156
	ds_read2_b32 v[80:81], v8 offset0:173 offset1:189
	ds_read2_b32 v[82:83], v8 offset0:206 offset1:222
	s_waitcnt lgkmcnt(4)
	v_max_f32_e32 v6, v28, v28
	s_waitcnt lgkmcnt(3)
	v_max_f32_e32 v10, v30, v30
	v_med3_f32 v6, v6, s39, v77
	v_med3_f32 v5, v10, s39, v77
	ds_read2_b32 v[84:85], v8 offset0:239 offset1:255
	v_cvt_pk_fp8_f32 v4, v6, v5 op_sel:[0,0,1]
	s_waitcnt lgkmcnt(3)
	v_max_f32_e32 v5, v32, v32
	s_waitcnt lgkmcnt(2)
	v_max_f32_e32 v6, v80, v80
	v_med3_f32 v8, v5, s39, v77
	v_med3_f32 v6, v6, s39, v77
	v_mov_b32_e32 v5, v35
	v_cvt_pk_fp8_f32 v5, v8, v6
	s_add_i32 s6, s4, 0xbd80
	s_lshr_b32 s6, s6, 1
	s_waitcnt lgkmcnt(1)
	v_max_f32_e32 v10, v82, v82
	s_waitcnt lgkmcnt(0)
	v_max_f32_e32 v6, v84, v84
	s_and_b32 s16, s6, 0x7fc0
	s_lshl_b32 s6, s4, 5
	v_med3_f32 v8, v10, s39, v77
	v_med3_f32 v6, v6, s39, v77
	s_and_b32 s6, s6, 0xfe0
	v_cvt_pk_fp8_f32 v5, v8, v6 op_sel:[0,0,1]
	v_or_b32_e32 v6, s6, v45
	v_lshl_add_u64 v[14:15], v[50:51], 0, s[16:17]
	v_lshlrev_b32_e32 v34, 9, v6
	v_lshl_add_u64 v[86:87], v[14:15], 0, v[34:35]
	global_store_dwordx4 v[86:87], v[2:5], off nt
	s_nop 1
	v_max_f32_e32 v2, v7, v7
	v_max_f32_e32 v3, v9, v9
	v_med3_f32 v5, v2, s39, v77
	v_med3_f32 v3, v3, s39, v77
	v_mov_b32_e32 v2, v35
	v_cvt_pk_fp8_f32 v2, v5, v3
	v_max_f32_e32 v4, v11, v11
	v_max_f32_e32 v3, v13, v13
	v_med3_f32 v4, v4, s39, v77
	v_med3_f32 v3, v3, s39, v77
	v_cvt_pk_fp8_f32 v2, v4, v3 op_sel:[0,0,1]
	v_max_f32_e32 v3, v17, v17
	v_max_f32_e32 v4, v19, v19
	v_med3_f32 v6, v3, s39, v77
	v_med3_f32 v4, v4, s39, v77
	v_mov_b32_e32 v3, v35
	v_cvt_pk_fp8_f32 v3, v6, v4
	v_max_f32_e32 v5, v21, v21
	v_max_f32_e32 v4, v23, v23
	v_med3_f32 v5, v5, s39, v77
	v_med3_f32 v4, v4, s39, v77
	v_cvt_pk_fp8_f32 v3, v5, v4 op_sel:[0,0,1]
	v_max_f32_e32 v4, v25, v25
	v_max_f32_e32 v5, v27, v27
	v_med3_f32 v7, v4, s39, v77
	v_med3_f32 v5, v5, s39, v77
	v_mov_b32_e32 v4, v35
	v_cvt_pk_fp8_f32 v4, v7, v5
	v_max_f32_e32 v6, v29, v29
	v_max_f32_e32 v5, v31, v31
	v_med3_f32 v6, v6, s39, v77
	v_med3_f32 v5, v5, s39, v77
	v_cvt_pk_fp8_f32 v4, v6, v5 op_sel:[0,0,1]
	v_max_f32_e32 v5, v33, v33
	v_max_f32_e32 v6, v81, v81
	v_med3_f32 v8, v5, s39, v77
	v_med3_f32 v6, v6, s39, v77
	v_mov_b32_e32 v5, v35
	v_cvt_pk_fp8_f32 v5, v8, v6
	v_max_f32_e32 v7, v83, v83
	v_max_f32_e32 v6, v85, v85
	v_med3_f32 v7, v7, s39, v77
	v_med3_f32 v6, v6, s39, v77
	v_cvt_pk_fp8_f32 v5, v7, v6 op_sel:[0,0,1]
	v_or_b32_e32 v6, s6, v62
	v_lshlrev_b32_e32 v34, 9, v6
	v_lshl_add_u64 v[6:7], v[14:15], 0, v[34:35]
	global_store_dwordx4 v[6:7], v[2:5], off nt
	s_waitcnt lgkmcnt(0)

.LBB0_75:
	s_waitcnt lgkmcnt(0)
	ds_read2_b32 v[6:7], v59 offset1:16
	ds_read2_b32 v[8:9], v59 offset0:33 offset1:49
	ds_read2_b32 v[10:11], v59 offset0:66 offset1:82
	ds_read2_b32 v[12:13], v59 offset0:99 offset1:115
	ds_read2_b32 v[16:17], v59 offset0:132 offset1:148
	ds_read2_b32 v[18:19], v59 offset0:165 offset1:181
	ds_read2_b32 v[20:21], v59 offset0:198 offset1:214
	ds_read2_b32 v[22:23], v59 offset0:231 offset1:247
	s_waitcnt lgkmcnt(7)
	v_max_f32_e32 v2, v6, v6
	s_waitcnt lgkmcnt(6)
	v_max_f32_e32 v3, v8, v8
	v_med3_f32 v6, v2, s39, v77
	v_med3_f32 v3, v3, s39, v77
	v_mov_b32_e32 v2, v35
	v_cvt_pk_fp8_f32 v2, v6, v3
	s_waitcnt lgkmcnt(5)
	v_max_f32_e32 v4, v10, v10
	s_waitcnt lgkmcnt(4)
	v_max_f32_e32 v5, v12, v12
	v_med3_f32 v4, v4, s39, v77
	v_med3_f32 v5, v5, s39, v77
	v_cvt_pk_fp8_f32 v2, v4, v5 op_sel:[0,0,1]
	s_waitcnt lgkmcnt(3)
	v_max_f32_e32 v3, v16, v16
	s_waitcnt lgkmcnt(2)
	v_max_f32_e32 v4, v18, v18
	v_med3_f32 v8, v3, s39, v77
	v_med3_f32 v4, v4, s39, v77
	v_mov_b32_e32 v3, v35
	v_cvt_pk_fp8_f32 v3, v8, v4
	v_add_u32_e32 v8, 0x400, v59
	ds_read2_b32 v[24:25], v8 offset0:8 offset1:24
	ds_read2_b32 v[26:27], v8 offset0:41 offset1:57
	ds_read2_b32 v[28:29], v8 offset0:74 offset1:90
	ds_read2_b32 v[30:31], v8 offset0:107 offset1:123
	s_waitcnt lgkmcnt(5)
	v_max_f32_e32 v5, v20, v20
	s_waitcnt lgkmcnt(4)
	v_max_f32_e32 v6, v22, v22
	v_med3_f32 v5, v5, s39, v77
	v_med3_f32 v6, v6, s39, v77
	v_cvt_pk_fp8_f32 v3, v5, v6 op_sel:[0,0,1]
	s_waitcnt lgkmcnt(3)
	v_max_f32_e32 v4, v24, v24
	s_waitcnt lgkmcnt(2)
	v_max_f32_e32 v5, v26, v26
	v_med3_f32 v12, v4, s39, v77
	v_med3_f32 v5, v5, s39, v77
	v_mov_b32_e32 v4, v35
	v_cvt_pk_fp8_f32 v4, v12, v5
	ds_read2_b32 v[32:33], v8 offset0:140 offset1:156
	ds_read2_b32 v[80:81], v8 offset0:173 offset1:189
	ds_read2_b32 v[82:83], v8 offset0:206 offset1:222
	s_waitcnt lgkmcnt(4)
	v_max_f32_e32 v6, v28, v28
	s_waitcnt lgkmcnt(3)
	v_max_f32_e32 v10, v30, v30
	v_med3_f32 v6, v6, s39, v77
	v_med3_f32 v5, v10, s39, v77
	ds_read2_b32 v[84:85], v8 offset0:239 offset1:255
	v_cvt_pk_fp8_f32 v4, v6, v5 op_sel:[0,0,1]
	s_waitcnt lgkmcnt(3)
	v_max_f32_e32 v5, v32, v32
	s_waitcnt lgkmcnt(2)
	v_max_f32_e32 v6, v80, v80
	v_med3_f32 v8, v5, s39, v77
	v_med3_f32 v6, v6, s39, v77
	v_mov_b32_e32 v5, v35
	v_cvt_pk_fp8_f32 v5, v8, v6
	s_waitcnt lgkmcnt(1)
	v_max_f32_e32 v10, v82, v82
	s_waitcnt lgkmcnt(0)
	v_max_f32_e32 v6, v84, v84
	v_med3_f32 v8, v10, s39, v77
	v_med3_f32 v6, v6, s39, v77
	s_and_b32 s6, 0xffff, s49
	v_cvt_pk_fp8_f32 v5, v8, v6 op_sel:[0,0,1]
	s_and_b32 s16, s47, 0xffff
	v_or_b32_e32 v6, s6, v45
	v_lshl_add_u64 v[14:15], v[52:53], 0, s[16:17]
	v_lshlrev_b32_e32 v34, 10, v6
	v_lshl_add_u64 v[86:87], v[14:15], 0, v[34:35]
	global_store_dwordx4 v[86:87], v[2:5], off nt
	s_nop 1
	v_max_f32_e32 v2, v7, v7
	v_max_f32_e32 v3, v9, v9
	v_med3_f32 v5, v2, s39, v77
	v_med3_f32 v3, v3, s39, v77
	v_mov_b32_e32 v2, v35
	v_cvt_pk_fp8_f32 v2, v5, v3
	v_max_f32_e32 v4, v11, v11
	v_max_f32_e32 v3, v13, v13
	v_med3_f32 v4, v4, s39, v77
	v_med3_f32 v3, v3, s39, v77
	v_cvt_pk_fp8_f32 v2, v4, v3 op_sel:[0,0,1]
	v_max_f32_e32 v3, v17, v17
	v_max_f32_e32 v4, v19, v19
	v_med3_f32 v6, v3, s39, v77
	v_med3_f32 v4, v4, s39, v77
	v_mov_b32_e32 v3, v35
	v_cvt_pk_fp8_f32 v3, v6, v4
	v_max_f32_e32 v5, v21, v21
	v_max_f32_e32 v4, v23, v23
	v_med3_f32 v5, v5, s39, v77
	v_med3_f32 v4, v4, s39, v77
	v_cvt_pk_fp8_f32 v3, v5, v4 op_sel:[0,0,1]
	v_max_f32_e32 v4, v25, v25
	v_max_f32_e32 v5, v27, v27
	v_med3_f32 v7, v4, s39, v77
	v_med3_f32 v5, v5, s39, v77
	v_mov_b32_e32 v4, v35
	v_cvt_pk_fp8_f32 v4, v7, v5
	v_max_f32_e32 v6, v29, v29
	v_max_f32_e32 v5, v31, v31
	v_med3_f32 v6, v6, s39, v77
	v_med3_f32 v5, v5, s39, v77
	v_cvt_pk_fp8_f32 v4, v6, v5 op_sel:[0,0,1]
	v_max_f32_e32 v5, v33, v33
	v_max_f32_e32 v6, v81, v81
	v_med3_f32 v8, v5, s39, v77
	v_med3_f32 v6, v6, s39, v77
	v_mov_b32_e32 v5, v35
	v_cvt_pk_fp8_f32 v5, v8, v6
	v_max_f32_e32 v7, v83, v83
	v_max_f32_e32 v6, v85, v85
	v_med3_f32 v7, v7, s39, v77
	v_med3_f32 v6, v6, s39, v77
	v_cvt_pk_fp8_f32 v5, v7, v6 op_sel:[0,0,1]
	v_or_b32_e32 v6, s6, v62
	v_lshlrev_b32_e32 v34, 10, v6
	v_lshl_add_u64 v[6:7], v[14:15], 0, v[34:35]
	global_store_dwordx4 v[6:7], v[2:5], off nt
	s_waitcnt lgkmcnt(0)

.LBB0_80:
	s_lshl_b32 s36, s7, 1
	s_lshl_b32 s37, s9, 1
	s_add_i32 s44, s36, 4
	s_add_i32 s45, s37, 4
	s_add_i32 s47, s36, 8
	s_add_i32 s49, s37, 8
	s_add_i32 s50, s36, 12
	s_add_i32 s51, s37, 12
	v_or_b32_e32 v8, s36, v3
	v_or_b32_e32 v6, s37, v2
	s_add_i32 s52, s36, 16
	s_add_i32 s53, s37, 16
	s_add_i32 s54, s36, 20
	s_add_i32 s55, s37, 20
	s_add_i32 s56, s36, 24
	s_add_i32 s57, s37, 24
	s_add_i32 s58, s36, 28
	s_add_i32 s59, s37, 28
	v_or_b32_e32 v12, s44, v3
	v_or_b32_e32 v10, s45, v2
	v_or_b32_e32 v16, s47, v3
	v_or_b32_e32 v14, s49, v2
	v_or_b32_e32 v20, s50, v3
	v_or_b32_e32 v18, s51, v2
	v_mad_i64_i32 v[6:7], s[26:27], v6, s46, v[4:5]
	v_mad_i64_i32 v[8:9], s[26:27], v8, s46, v[4:5]
	v_or_b32_e32 v24, s52, v3
	v_or_b32_e32 v22, s53, v2
	v_or_b32_e32 v28, s54, v3
	v_or_b32_e32 v26, s55, v2
	v_or_b32_e32 v32, s56, v3
	v_or_b32_e32 v30, s57, v2
	v_or_b32_e32 v34, s58, v3
	v_or_b32_e32 v61, s59, v2
	v_mad_i64_i32 v[10:11], s[26:27], v10, s46, v[4:5]
	v_mad_i64_i32 v[12:13], s[26:27], v12, s46, v[4:5]
	v_mad_i64_i32 v[14:15], s[26:27], v14, s46, v[4:5]
	v_mad_i64_i32 v[16:17], s[26:27], v16, s46, v[4:5]
	v_mad_i64_i32 v[18:19], s[26:27], v18, s46, v[4:5]
	v_mad_i64_i32 v[20:21], s[26:27], v20, s46, v[4:5]
	v_mad_i64_i32 v[22:23], s[26:27], v22, s46, v[4:5]
	v_mad_i64_i32 v[24:25], s[26:27], v24, s46, v[4:5]
	v_mad_i64_i32 v[26:27], s[26:27], v26, s46, v[4:5]
	v_mad_i64_i32 v[28:29], s[26:27], v28, s46, v[4:5]
	v_mad_i64_i32 v[30:31], s[26:27], v30, s46, v[4:5]
	v_mad_i64_i32 v[32:33], s[26:27], v32, s46, v[4:5]
	v_mad_i64_i32 v[80:81], s[26:27], v61, s46, v[4:5]
	v_mad_i64_i32 v[82:83], s[26:27], v34, s46, v[4:5]
	global_load_dword v6, v[6:7], off
	s_nop 0
	global_load_dword v7, v[8:9], off
	s_nop 0
	global_load_dword v8, v[10:11], off
	global_load_dword v9, v[12:13], off
	s_nop 0
	global_load_dword v10, v[14:15], off
	global_load_dword v11, v[16:17], off
	global_load_dword v12, v[18:19], off
	global_load_dword v13, v[20:21], off
	s_nop 0
	global_load_dword v14, v[22:23], off
	global_load_dword v15, v[24:25], off
	global_load_dword v16, v[26:27], off
	global_load_dword v17, v[28:29], off
	global_load_dword v18, v[30:31], off
	global_load_dword v19, v[32:33], off
	global_load_dword v20, v[80:81], off
	global_load_dword v21, v[82:83], off
	v_or_b32_e32 v24, s36, v1
	v_or_b32_e32 v22, s37, v38
	v_mad_u64_u32 v[24:25], s[26:27], v24, s21, v[44:45]
	s_add_i32 s9, s9, 16
	s_add_i32 s7, s7, 16
	s_add_i32 s16, s16, -16
	v_mad_u64_u32 v[22:23], s[26:27], v22, s21, v[44:45]
	v_or_b32_e32 v25, s45, v38
	v_or_b32_e32 v23, s44, v1
	v_or_b32_e32 v32, s47, v1
	v_or_b32_e32 v30, s49, v38
	v_or_b32_e32 v34, s50, v1
	v_or_b32_e32 v61, s51, v38
	v_or_b32_e32 v79, s52, v1
	v_or_b32_e32 v84, s53, v38
	v_or_b32_e32 v90, s54, v1
	v_or_b32_e32 v88, s55, v38
	v_or_b32_e32 v94, s56, v1
	v_or_b32_e32 v92, s57, v38
	v_or_b32_e32 v98, s58, v1
	v_or_b32_e32 v96, s59, v38
	s_cmp_lg_u32 s16, 0
	v_mad_u64_u32 v[26:27], s[26:27], v25, s21, v[44:45]
	v_mad_u64_u32 v[28:29], s[26:27], v23, s21, v[44:45]
	v_mad_u64_u32 v[30:31], s[26:27], v30, s21, v[44:45]
	v_mad_u64_u32 v[32:33], s[26:27], v32, s21, v[44:45]
	v_mad_u64_u32 v[80:81], s[26:27], v61, s21, v[44:45]
	v_mad_u64_u32 v[82:83], s[26:27], v34, s21, v[44:45]
	v_mad_u64_u32 v[84:85], s[26:27], v84, s21, v[44:45]
	v_mad_u64_u32 v[86:87], s[26:27], v79, s21, v[44:45]
	v_mad_u64_u32 v[88:89], s[26:27], v88, s21, v[44:45]
	v_mad_u64_u32 v[90:91], s[26:27], v90, s21, v[44:45]
	v_mad_u64_u32 v[92:93], s[26:27], v92, s21, v[44:45]
	v_mad_u64_u32 v[94:95], s[26:27], v94, s21, v[44:45]
	v_mad_u64_u32 v[96:97], s[26:27], v96, s21, v[44:45]
	v_mad_u64_u32 v[98:99], s[26:27], v98, s21, v[44:45]
	s_waitcnt vmcnt(14)
	v_pk_mul_f32 v[6:7], v[6:7], s[24:25] op_sel_hi:[1,0]
	ds_write_b32 v22, v6
	ds_write_b32 v24, v7
	s_waitcnt vmcnt(12)
	v_pk_mul_f32 v[6:7], v[8:9], s[24:25] op_sel_hi:[1,0]
	s_waitcnt vmcnt(10)
	v_pk_mul_f32 v[8:9], v[10:11], s[24:25] op_sel_hi:[1,0]
	s_waitcnt vmcnt(8)
	v_pk_mul_f32 v[10:11], v[12:13], s[24:25] op_sel_hi:[1,0]
	s_waitcnt vmcnt(6)
	v_pk_mul_f32 v[12:13], v[14:15], s[24:25] op_sel_hi:[1,0]
	s_waitcnt vmcnt(4)
	v_pk_mul_f32 v[14:15], v[16:17], s[24:25] op_sel_hi:[1,0]
	s_waitcnt vmcnt(2)
	v_pk_mul_f32 v[16:17], v[18:19], s[24:25] op_sel_hi:[1,0]
	s_waitcnt vmcnt(0)
	v_pk_mul_f32 v[18:19], v[20:21], s[24:25] op_sel_hi:[1,0]
	ds_write_b32 v26, v6
	ds_write_b32 v28, v7
	ds_write_b32 v30, v8
	ds_write_b32 v32, v9
	ds_write_b32 v80, v10
	ds_write_b32 v82, v11
	ds_write_b32 v84, v12
	ds_write_b32 v86, v13
	ds_write_b32 v88, v14
	ds_write_b32 v90, v15
	ds_write_b32 v92, v16
	ds_write_b32 v94, v17
	ds_write_b32 v96, v18
	ds_write_b32 v98, v19
	s_cbranch_scc1 .LBB0_80
	s_waitcnt lgkmcnt(0)
	ds_read2_b32 v[8:9], v59 offset1:16
	ds_read2_b32 v[10:11], v59 offset0:33 offset1:49
	ds_read2_b32 v[12:13], v59 offset0:66 offset1:82
	ds_read2_b32 v[14:15], v59 offset0:99 offset1:115
	ds_read2_b32 v[18:19], v59 offset0:132 offset1:148
	ds_read2_b32 v[20:21], v59 offset0:165 offset1:181
	ds_read2_b32 v[22:23], v59 offset0:198 offset1:214
	ds_read2_b32 v[24:25], v59 offset0:231 offset1:247
	s_waitcnt lgkmcnt(7)
	v_max_f32_e32 v4, v8, v8
	s_waitcnt lgkmcnt(6)
	v_max_f32_e32 v5, v10, v10
	v_med3_f32 v8, v4, s39, v77
	v_med3_f32 v5, v5, s39, v77
	v_mov_b32_e32 v4, v35
	v_cvt_pk_fp8_f32 v4, v8, v5
	s_waitcnt lgkmcnt(5)
	v_max_f32_e32 v6, v12, v12
	s_waitcnt lgkmcnt(4)
	v_max_f32_e32 v7, v14, v14
	v_med3_f32 v6, v6, s39, v77
	v_med3_f32 v7, v7, s39, v77
	v_cvt_pk_fp8_f32 v4, v6, v7 op_sel:[0,0,1]
	s_waitcnt lgkmcnt(3)
	v_max_f32_e32 v5, v18, v18
	s_waitcnt lgkmcnt(2)
	v_max_f32_e32 v6, v20, v20
	v_med3_f32 v10, v5, s39, v77
	v_med3_f32 v6, v6, s39, v77
	v_mov_b32_e32 v5, v35
	v_cvt_pk_fp8_f32 v5, v10, v6
	v_add_u32_e32 v10, 0x400, v59
	ds_read2_b32 v[26:27], v10 offset0:8 offset1:24
	ds_read2_b32 v[28:29], v10 offset0:41 offset1:57
	ds_read2_b32 v[30:31], v10 offset0:74 offset1:90
	ds_read2_b32 v[32:33], v10 offset0:107 offset1:123
	s_waitcnt lgkmcnt(5)
	v_max_f32_e32 v7, v22, v22
	s_waitcnt lgkmcnt(4)
	v_max_f32_e32 v8, v24, v24
	v_med3_f32 v7, v7, s39, v77
	v_med3_f32 v8, v8, s39, v77
	v_cvt_pk_fp8_f32 v5, v7, v8 op_sel:[0,0,1]
	s_waitcnt lgkmcnt(3)
	v_max_f32_e32 v6, v26, v26
	s_waitcnt lgkmcnt(2)
	v_max_f32_e32 v7, v28, v28
	v_med3_f32 v14, v6, s39, v77
	v_med3_f32 v7, v7, s39, v77
	v_mov_b32_e32 v6, v35
	v_cvt_pk_fp8_f32 v6, v14, v7
	ds_read2_b32 v[80:81], v10 offset0:140 offset1:156
	ds_read2_b32 v[82:83], v10 offset0:173 offset1:189
	ds_read2_b32 v[84:85], v10 offset0:206 offset1:222
	s_waitcnt lgkmcnt(4)
	v_max_f32_e32 v8, v30, v30
	s_waitcnt lgkmcnt(3)
	v_max_f32_e32 v12, v32, v32
	v_med3_f32 v8, v8, s39, v77
	v_med3_f32 v7, v12, s39, v77
	ds_read2_b32 v[86:87], v10 offset0:239 offset1:255
	v_cvt_pk_fp8_f32 v6, v8, v7 op_sel:[0,0,1]
	s_waitcnt lgkmcnt(3)
	v_max_f32_e32 v7, v80, v80
	s_waitcnt lgkmcnt(2)
	v_max_f32_e32 v8, v82, v82
	v_med3_f32 v10, v7, s39, v77
	v_med3_f32 v8, v8, s39, v77
	v_mov_b32_e32 v7, v35
	v_cvt_pk_fp8_f32 v7, v10, v8
	s_waitcnt lgkmcnt(1)
	v_max_f32_e32 v12, v84, v84
	s_waitcnt lgkmcnt(0)
	v_max_f32_e32 v8, v86, v86
	v_med3_f32 v10, v12, s39, v77
	v_med3_f32 v8, v8, s39, v77
	v_cvt_pk_fp8_f32 v7, v10, v8 op_sel:[0,0,1]
	s_ashr_i32 s9, s8, 31
	v_or_b32_e32 v34, s6, v45
	v_lshl_add_u64 v[16:17], v[54:55], 0, s[8:9]
	v_lshlrev_b64 v[88:89], 12, v[34:35]
	v_lshl_add_u64 v[88:89], v[16:17], 0, v[88:89]
	global_store_dwordx4 v[88:89], v[4:7], off nt
	v_or_b32_e32 v34, s6, v62
	s_mov_b64 s[26:27], 0
	v_max_f32_e32 v4, v9, v9
	v_max_f32_e32 v5, v11, v11
	v_med3_f32 v7, v4, s39, v77
	v_med3_f32 v5, v5, s39, v77
	v_mov_b32_e32 v4, v35
	v_cvt_pk_fp8_f32 v4, v7, v5
	v_max_f32_e32 v6, v13, v13
	v_max_f32_e32 v5, v15, v15
	v_med3_f32 v6, v6, s39, v77
	v_med3_f32 v5, v5, s39, v77
	v_cvt_pk_fp8_f32 v4, v6, v5 op_sel:[0,0,1]
	v_max_f32_e32 v5, v19, v19
	v_max_f32_e32 v6, v21, v21
	v_med3_f32 v8, v5, s39, v77
	v_med3_f32 v6, v6, s39, v77
	v_mov_b32_e32 v5, v35
	v_cvt_pk_fp8_f32 v5, v8, v6
	v_max_f32_e32 v7, v23, v23
	v_max_f32_e32 v6, v25, v25
	v_med3_f32 v7, v7, s39, v77
	v_med3_f32 v6, v6, s39, v77
	v_cvt_pk_fp8_f32 v5, v7, v6 op_sel:[0,0,1]
	v_max_f32_e32 v6, v27, v27
	v_max_f32_e32 v7, v29, v29
	v_med3_f32 v9, v6, s39, v77
	v_med3_f32 v7, v7, s39, v77
	v_mov_b32_e32 v6, v35
	v_cvt_pk_fp8_f32 v6, v9, v7
	v_max_f32_e32 v8, v31, v31
	v_max_f32_e32 v7, v33, v33
	v_med3_f32 v8, v8, s39, v77
	v_med3_f32 v7, v7, s39, v77
	v_cvt_pk_fp8_f32 v6, v8, v7 op_sel:[0,0,1]
	v_max_f32_e32 v7, v81, v81
	v_max_f32_e32 v8, v83, v83
	v_med3_f32 v10, v7, s39, v77
	v_med3_f32 v8, v8, s39, v77
	v_mov_b32_e32 v7, v35
	v_cvt_pk_fp8_f32 v7, v10, v8
	v_max_f32_e32 v9, v85, v85
	v_max_f32_e32 v8, v87, v87
	v_med3_f32 v9, v9, s39, v77
	v_med3_f32 v8, v8, s39, v77
	v_cvt_pk_fp8_f32 v7, v9, v8 op_sel:[0,0,1]
	v_lshlrev_b64 v[8:9], 12, v[34:35]
	v_lshl_add_u64 v[8:9], v[16:17], 0, v[8:9]
	global_store_dwordx4 v[8:9], v[4:7], off nt
	s_waitcnt lgkmcnt(0)

.LBB0_84:
	s_lshl_b32 s11, s7, 1
	s_lshl_b32 s16, s9, 1
	v_or_b32_e32 v6, s16, v2
	s_add_i32 s36, s11, 4
	s_add_i32 s37, s16, 4
	s_add_i32 s44, s11, 8
	s_add_i32 s45, s16, 8
	s_add_i32 s47, s11, 12
	s_add_i32 s49, s16, 12
	s_add_i32 s50, s11, 16
	s_add_i32 s51, s16, 16
	s_add_i32 s52, s11, 20
	s_add_i32 s53, s16, 20
	s_add_i32 s54, s11, 24
	s_add_i32 s55, s16, 24
	s_add_i32 s56, s11, 28
	s_add_i32 s57, s16, 28
	v_or_b32_e32 v8, s11, v3
	v_mad_i64_i32 v[6:7], s[26:27], v6, s46, v[4:5]
	v_or_b32_e32 v12, s36, v3
	v_or_b32_e32 v10, s37, v2
	v_or_b32_e32 v16, s44, v3
	v_or_b32_e32 v14, s45, v2
	v_or_b32_e32 v20, s47, v3
	v_or_b32_e32 v18, s49, v2
	v_or_b32_e32 v24, s50, v3
	v_or_b32_e32 v22, s51, v2
	v_or_b32_e32 v28, s52, v3
	v_or_b32_e32 v26, s53, v2
	v_or_b32_e32 v32, s54, v3
	v_or_b32_e32 v30, s55, v2
	v_or_b32_e32 v34, s56, v3
	v_or_b32_e32 v61, s57, v2
	v_mad_i64_i32 v[8:9], s[26:27], v8, s46, v[4:5]
	v_mad_i64_i32 v[10:11], s[26:27], v10, s46, v[4:5]
	v_mad_i64_i32 v[12:13], s[26:27], v12, s46, v[4:5]
	v_mad_i64_i32 v[14:15], s[26:27], v14, s46, v[4:5]
	v_mad_i64_i32 v[16:17], s[26:27], v16, s46, v[4:5]
	v_mad_i64_i32 v[18:19], s[26:27], v18, s46, v[4:5]
	v_mad_i64_i32 v[20:21], s[26:27], v20, s46, v[4:5]
	v_mad_i64_i32 v[22:23], s[26:27], v22, s46, v[4:5]
	v_mad_i64_i32 v[24:25], s[26:27], v24, s46, v[4:5]
	v_mad_i64_i32 v[26:27], s[26:27], v26, s46, v[4:5]
	v_mad_i64_i32 v[28:29], s[26:27], v28, s46, v[4:5]
	v_mad_i64_i32 v[30:31], s[26:27], v30, s46, v[4:5]
	v_mad_i64_i32 v[32:33], s[26:27], v32, s46, v[4:5]
	v_mad_i64_i32 v[80:81], s[26:27], v61, s46, v[4:5]
	v_mad_i64_i32 v[82:83], s[26:27], v34, s46, v[4:5]
	global_load_dword v34, v[6:7], off
	global_load_dword v61, v[8:9], off
	global_load_dword v79, v[10:11], off
	global_load_dword v84, v[12:13], off
	global_load_dword v85, v[14:15], off
	global_load_dword v86, v[16:17], off
	global_load_dword v87, v[18:19], off
	global_load_dword v88, v[20:21], off
	global_load_dword v89, v[22:23], off
	global_load_dword v90, v[24:25], off
	global_load_dword v91, v[26:27], off
	global_load_dword v92, v[28:29], off
	global_load_dword v93, v[30:31], off
	global_load_dword v94, v[32:33], off
	global_load_dword v95, v[80:81], off
	global_load_dword v96, v[82:83], off
	v_or_b32_e32 v8, s11, v1
	v_or_b32_e32 v6, s16, v38
	s_add_i32 s9, s9, 16
	s_add_i32 s7, s7, 16
	s_add_i32 s10, s10, -16
	v_mad_u64_u32 v[6:7], s[26:27], v6, s21, v[44:45]
	v_mad_u64_u32 v[8:9], s[26:27], v8, s21, v[44:45]
	v_or_b32_e32 v7, s36, v1
	v_or_b32_e32 v9, s37, v38
	v_or_b32_e32 v16, s44, v1
	v_or_b32_e32 v14, s45, v38
	v_or_b32_e32 v20, s47, v1
	v_or_b32_e32 v18, s49, v38
	v_or_b32_e32 v24, s50, v1
	v_or_b32_e32 v22, s51, v38
	v_or_b32_e32 v28, s52, v1
	v_or_b32_e32 v26, s53, v38
	v_or_b32_e32 v32, s54, v1
	v_or_b32_e32 v30, s55, v38
	v_or_b32_e32 v82, s56, v1
	v_or_b32_e32 v80, s57, v38
	s_cmp_lg_u32 s10, 0
	v_mad_u64_u32 v[10:11], s[26:27], v9, s21, v[44:45]
	v_mad_u64_u32 v[12:13], s[26:27], v7, s21, v[44:45]
	v_mad_u64_u32 v[14:15], s[26:27], v14, s21, v[44:45]
	v_mad_u64_u32 v[16:17], s[26:27], v16, s21, v[44:45]
	v_mad_u64_u32 v[18:19], s[26:27], v18, s21, v[44:45]
	v_mad_u64_u32 v[20:21], s[26:27], v20, s21, v[44:45]
	v_mad_u64_u32 v[22:23], s[26:27], v22, s21, v[44:45]
	v_mad_u64_u32 v[24:25], s[26:27], v24, s21, v[44:45]
	v_mad_u64_u32 v[26:27], s[26:27], v26, s21, v[44:45]
	v_mad_u64_u32 v[28:29], s[26:27], v28, s21, v[44:45]
	v_mad_u64_u32 v[30:31], s[26:27], v30, s21, v[44:45]
	v_mad_u64_u32 v[32:33], s[26:27], v32, s21, v[44:45]
	v_mad_u64_u32 v[80:81], s[26:27], v80, s21, v[44:45]
	v_mad_u64_u32 v[82:83], s[26:27], v82, s21, v[44:45]
	s_waitcnt vmcnt(15)
	ds_write_b32 v6, v34
	s_waitcnt vmcnt(14)
	ds_write_b32 v8, v61
	s_waitcnt vmcnt(13)
	ds_write_b32 v10, v79
	s_waitcnt vmcnt(12)
	ds_write_b32 v12, v84
	s_waitcnt vmcnt(11)
	ds_write_b32 v14, v85
	s_waitcnt vmcnt(10)
	ds_write_b32 v16, v86
	s_waitcnt vmcnt(9)
	ds_write_b32 v18, v87
	s_waitcnt vmcnt(8)
	ds_write_b32 v20, v88
	s_waitcnt vmcnt(7)
	ds_write_b32 v22, v89
	s_waitcnt vmcnt(6)
	ds_write_b32 v24, v90
	s_waitcnt vmcnt(5)
	ds_write_b32 v26, v91
	s_waitcnt vmcnt(4)
	ds_write_b32 v28, v92
	s_waitcnt vmcnt(3)
	ds_write_b32 v30, v93
	s_waitcnt vmcnt(2)
	ds_write_b32 v32, v94
	s_waitcnt vmcnt(1)
	ds_write_b32 v80, v95
	s_waitcnt vmcnt(0)
	ds_write_b32 v82, v96
	s_cbranch_scc1 .LBB0_84
	s_waitcnt lgkmcnt(0)
	ds_read2_b32 v[6:7], v65 offset1:8
	ds_read2_b32 v[10:11], v65 offset0:33 offset1:41
	ds_read2_b32 v[12:13], v65 offset0:66 offset1:74
	ds_read2_b32 v[14:15], v65 offset0:99 offset1:107
	ds_read2_b32 v[16:17], v65 offset0:132 offset1:140
	ds_read2_b32 v[18:19], v65 offset0:165 offset1:173
	s_waitcnt lgkmcnt(5)
	v_bfe_u32 v2, v6, 16, 1
	v_add3_u32 v2, v6, v2, s41
	s_waitcnt lgkmcnt(4)
	v_bfe_u32 v3, v10, 16, 1
	v_lshrrev_b32_e32 v2, 16, v2
	v_add3_u32 v3, v10, v3, s41
	v_and_or_b32 v2, v3, s42, v2
	s_waitcnt lgkmcnt(3)
	v_bfe_u32 v3, v12, 16, 1
	v_add3_u32 v3, v12, v3, s41
	s_waitcnt lgkmcnt(2)
	v_bfe_u32 v4, v14, 16, 1
	ds_read2_b32 v[20:21], v65 offset0:198 offset1:206
	v_lshrrev_b32_e32 v3, 16, v3
	v_add3_u32 v4, v14, v4, s41
	ds_read2_b32 v[22:23], v65 offset0:231 offset1:239
	v_and_or_b32 v3, v4, s42, v3
	s_waitcnt lgkmcnt(3)
	v_bfe_u32 v4, v16, 16, 1
	v_add3_u32 v4, v16, v4, s41
	s_waitcnt lgkmcnt(2)
	v_bfe_u32 v5, v18, 16, 1
	v_lshrrev_b32_e32 v4, 16, v4
	v_add3_u32 v5, v18, v5, s41
	v_and_or_b32 v4, v5, s42, v4
	s_waitcnt lgkmcnt(1)
	v_bfe_u32 v5, v20, 16, 1
	v_or_b32_e32 v24, s6, v64
	s_ashr_i32 s9, s8, 31
	v_add3_u32 v5, v20, v5, s41
	s_waitcnt lgkmcnt(0)
	v_bfe_u32 v6, v22, 16, 1
	v_ashrrev_i32_e32 v25, 31, v24
	v_lshl_add_u64 v[8:9], s[8:9], 1, v[56:57]
	v_lshrrev_b32_e32 v5, 16, v5
	v_add3_u32 v6, v22, v6, s41
	v_lshlrev_b64 v[24:25], 13, v[24:25]
	v_and_or_b32 v5, v6, s42, v5
	v_lshl_add_u64 v[24:25], v[8:9], 0, v[24:25]
	global_store_dwordx4 v[24:25], v[2:5], off nt
	v_bfe_u32 v6, v23, 16, 1
	v_add3_u32 v6, v23, v6, s41
	v_bfe_u32 v2, v7, 16, 1
	v_add3_u32 v2, v7, v2, s41
	v_bfe_u32 v3, v11, 16, 1
	v_lshrrev_b32_e32 v2, 16, v2
	v_add3_u32 v3, v11, v3, s41
	v_and_or_b32 v2, v3, s42, v2
	v_bfe_u32 v3, v13, 16, 1
	v_add3_u32 v3, v13, v3, s41
	v_bfe_u32 v4, v15, 16, 1
	v_lshrrev_b32_e32 v3, 16, v3
	v_add3_u32 v4, v15, v4, s41
	v_and_or_b32 v3, v4, s42, v3
	v_bfe_u32 v4, v17, 16, 1
	v_add3_u32 v4, v17, v4, s41
	v_bfe_u32 v5, v19, 16, 1
	v_lshrrev_b32_e32 v4, 16, v4
	v_add3_u32 v5, v19, v5, s41
	v_and_or_b32 v4, v5, s42, v4
	v_bfe_u32 v5, v21, 16, 1
	v_add3_u32 v5, v21, v5, s41
	v_lshrrev_b32_e32 v5, 16, v5
	v_and_or_b32 v5, v6, s42, v5
	v_or_b32_e32 v6, s6, v66
	v_ashrrev_i32_e32 v7, 31, v6
	v_lshlrev_b64 v[6:7], 13, v[6:7]
	ds_read2_b32 v[10:11], v65 offset0:16 offset1:24
	v_lshl_add_u64 v[6:7], v[8:9], 0, v[6:7]
	global_store_dwordx4 v[6:7], v[2:5], off nt
	ds_read2_b32 v[6:7], v65 offset0:49 offset1:57
	ds_read2_b32 v[12:13], v65 offset0:82 offset1:90
	ds_read2_b32 v[14:15], v65 offset0:115 offset1:123
	s_waitcnt lgkmcnt(3)
	v_bfe_u32 v2, v10, 16, 1
	v_add3_u32 v2, v10, v2, s41
	s_waitcnt lgkmcnt(2)
	v_bfe_u32 v3, v6, 16, 1
	ds_read2_b32 v[16:17], v65 offset0:148 offset1:156
	v_lshrrev_b32_e32 v2, 16, v2
	v_add3_u32 v3, v6, v3, s41
	ds_read2_b32 v[18:19], v65 offset0:181 offset1:189
	v_and_or_b32 v2, v3, s42, v2
	s_waitcnt lgkmcnt(3)
	v_bfe_u32 v3, v12, 16, 1
	v_add3_u32 v3, v12, v3, s41
	s_waitcnt lgkmcnt(2)
	v_bfe_u32 v4, v14, 16, 1
	ds_read2_b32 v[20:21], v65 offset0:214 offset1:222
	v_lshrrev_b32_e32 v3, 16, v3
	v_add3_u32 v4, v14, v4, s41
	ds_read2_b32 v[22:23], v65 offset0:247 offset1:255
	v_and_or_b32 v3, v4, s42, v3
	s_waitcnt lgkmcnt(3)
	v_bfe_u32 v4, v16, 16, 1
	v_add3_u32 v4, v16, v4, s41
	s_waitcnt lgkmcnt(2)
	v_bfe_u32 v5, v18, 16, 1
	v_lshrrev_b32_e32 v4, 16, v4
	v_add3_u32 v5, v18, v5, s41
	v_and_or_b32 v4, v5, s42, v4
	s_waitcnt lgkmcnt(1)
	v_bfe_u32 v5, v20, 16, 1
	v_or_b32_e32 v24, s6, v67
	v_add3_u32 v5, v20, v5, s41
	s_waitcnt lgkmcnt(0)
	v_bfe_u32 v6, v22, 16, 1
	v_ashrrev_i32_e32 v25, 31, v24
	v_lshrrev_b32_e32 v5, 16, v5
	v_add3_u32 v6, v22, v6, s41
	v_lshlrev_b64 v[24:25], 13, v[24:25]
	v_and_or_b32 v5, v6, s42, v5
	v_lshl_add_u64 v[24:25], v[8:9], 0, v[24:25]
	global_store_dwordx4 v[24:25], v[2:5], off nt
	v_bfe_u32 v6, v23, 16, 1
	v_add3_u32 v6, v23, v6, s41
	v_bfe_u32 v2, v11, 16, 1
	v_add3_u32 v2, v11, v2, s41
	v_bfe_u32 v3, v7, 16, 1
	v_lshrrev_b32_e32 v2, 16, v2
	v_add3_u32 v3, v7, v3, s41
	v_and_or_b32 v2, v3, s42, v2
	v_bfe_u32 v3, v13, 16, 1
	v_add3_u32 v3, v13, v3, s41
	v_bfe_u32 v4, v15, 16, 1
	v_lshrrev_b32_e32 v3, 16, v3
	v_add3_u32 v4, v15, v4, s41
	v_and_or_b32 v3, v4, s42, v3
	v_bfe_u32 v4, v17, 16, 1
	v_add3_u32 v4, v17, v4, s41
	v_bfe_u32 v5, v19, 16, 1
	v_lshrrev_b32_e32 v4, 16, v4
	v_add3_u32 v5, v19, v5, s41
	v_and_or_b32 v4, v5, s42, v4
	v_bfe_u32 v5, v21, 16, 1
	v_add3_u32 v5, v21, v5, s41
	v_lshrrev_b32_e32 v5, 16, v5
	v_and_or_b32 v5, v6, s42, v5
	v_or_b32_e32 v6, s6, v68
	v_ashrrev_i32_e32 v7, 31, v6
	v_lshlrev_b64 v[6:7], 13, v[6:7]
	v_lshl_add_u64 v[6:7], v[8:9], 0, v[6:7]
	global_store_dwordx4 v[6:7], v[2:5], off nt
	s_waitcnt lgkmcnt(0)
	s_branch .LBB0_11

.LBB0_88:
	v_lshl_add_u64 v[6:7], v[6:7], 0, s[8:9]
	v_cmp_lt_u64_e32 vcc, s[18:19], v[6:7]
	global_store_dwordx4 v[8:9], v[2:5], off nt
	s_or_b64 s[16:17], vcc, s[16:17]
	v_lshl_add_u64 v[8:9], v[8:9], 0, s[10:11]
	s_andn2_b64 exec, exec, s[16:17]
	s_cbranch_execnz .LBB0_88
